# w2 + one static s_setprio 1 for the lagging wave half (waves 4-7) across the attention main loop
# speedup vs baseline: 1.0089x; 1.0089x over previous
; __device__ __forceinline__ void attn_pv(unsigned vaddr, const int (&vo)[8], const bf16x8 (&pf)[2][2], f32x4 (&o)[2][8], f32x4 (&ol)[2]) {
;     s16x4 r[3][4];
;     ...
;     AT_TR4(0, 0); AT_TR4(1, 1);
;     { const bf16x8 ones = (bf16x8){0x3f80, 0x3f80, 0x3f80, 0x3f80, 0x3f80, 0x3f80, 0x3f80, 0x3f80};
; #pragma unroll
;       for (int c = 0; c < 2; ++c)
; #pragma unroll
;           for (int si = 0; si < 2; ++si) ol[c] = __builtin_amdgcn_mfma_f32_16x16x32_bf16(ones, pf[c][si], ol[c], 0, 0, 0); }
; #pragma unroll
;     for (int dt = 0; dt < 8; ++dt) {
;         const int cb = dt % 3;
;         if (dt < 6) { AT_TR4((dt + 2) % 3, dt + 2); asm volatile("s_waitcnt lgkmcnt(8)" : "+v"(r[cb][0]), "+v"(r[cb][1]), "+v"(r[cb][2]), "+v"(r[cb][3])); }
;         else if (dt == 6) asm volatile("s_waitcnt lgkmcnt(4)" : "+v"(r[cb][0]), "+v"(r[cb][1]), "+v"(r[cb][2]), "+v"(r[cb][3]));
;         else asm volatile("s_waitcnt lgkmcnt(0)" : "+v"(r[cb][0]), "+v"(r[cb][1]), "+v"(r[cb][2]), "+v"(r[cb][3]));
; #pragma unroll
;         for (int si = 0; si < 2; ++si) {
;             const s16x4 lo = r[cb][2 * si], hi = r[cb][2 * si + 1];
;             const bf16x8 vf = (bf16x8){lo[0], lo[1], lo[2], lo[3], hi[0], hi[1], hi[2], hi[3]};
;             o[0][dt] = __builtin_amdgcn_mfma_f32_16x16x32_bf16(vf, pf[0][si], o[0][dt], 0, 0, 0);
;             o[1][dt] = __builtin_amdgcn_mfma_f32_16x16x32_bf16(vf, pf[1][si], o[1][dt], 0, 0, 0);
;         }
;     }
;     ...
; }
; template <bool QK, bool PV> ...
;     ...
;     if constexpr (PV) { AT_TR4(0, 0); AT_TR4(1, 1);
;         const bf16x8 ones = (bf16x8){0x3f80, 0x3f80, 0x3f80, 0x3f80, 0x3f80, 0x3f80, 0x3f80, 0x3f80};
; #pragma unroll
;         for (int c = 0; c < 2; ++c)
; #pragma unroll
;             for (int si = 0; si < 2; ++si) ol[c] = __builtin_amdgcn_mfma_f32_16x16x32_bf16(ones, pf[c][si], ol[c], 0, 0, 0); }
; #pragma unroll
;     for (int dt = 0; dt < 8; ++dt) {
;         if constexpr (PV) {
;             const int cb = dt % 3;
;             if (dt < 6) { AT_TR4((dt + 2) % 3, dt + 2); asm volatile("s_waitcnt lgkmcnt(8)" : "+v"(r[cb][0]), "+v"(r[cb][1]), "+v"(r[cb][2]), "+v"(r[cb][3])); }
;             else if (dt == 6) asm volatile("s_waitcnt lgkmcnt(4)" : "+v"(r[cb][0]), "+v"(r[cb][1]), "+v"(r[cb][2]), "+v"(r[cb][3]));
;             else asm volatile("s_waitcnt lgkmcnt(0)" : "+v"(r[cb][0]), "+v"(r[cb][1]), "+v"(r[cb][2]), "+v"(r[cb][3]));
; #pragma unroll
.Lat_yskip_s:
	s_setprio 0
	v_mov_b64_e32 v[140:141], s[6:7]
	v_mov_b64_e32 v[138:139], s[4:5]
	ds_read_b64_tr_b16 v[2:3], v194 offset:0
	ds_read_b64_tr_b16 v[4:5], v194 offset:0x1000
	ds_read_b64_tr_b16 v[10:11], v194 offset:0x2000
	ds_read_b64_tr_b16 v[12:13], v194 offset:0x3000
	v_exp_f32_e32 v154, v74
	s_nop 0
	v_mfma_f32_16x16x32_bf16 v[6:9], v[138:141], v[58:61], v[134:137]
	v_exp_f32_e32 v161, v75
	v_exp_f32_e32 v90, v90
	v_exp_f32_e32 v91, v91
	v_mfma_f32_16x16x32_bf16 v[134:137], v[138:141], v[34:37], v[6:9]
	ds_read_b64_tr_b16 v[6:7], v195 offset:0
	ds_read_b64_tr_b16 v[8:9], v195 offset:0x1000
	ds_read_b64_tr_b16 v[14:15], v195 offset:0x2000
	ds_read_b64_tr_b16 v[16:17], v195 offset:0x3000
	ds_read_b64_tr_b16 v[142:143], v196 offset:0
	ds_read_b64_tr_b16 v[144:145], v196 offset:0x1000
	ds_read_b64_tr_b16 v[146:147], v196 offset:0x2000
	ds_read_b64_tr_b16 v[148:149], v196 offset:0x3000
	s_waitcnt lgkmcnt(8)
	ds_read_b64_tr_b16 v[150:151], v197 offset:0
	ds_read_b64_tr_b16 v[152:153], v197 offset:0x1000
	v_mfma_f32_16x16x32_bf16 v[130:133], v[138:141], v[42:45], v[130:133]
	v_exp_f32_e32 v92, v92
	v_exp_f32_e32 v93, v93
	v_exp_f32_e32 v94, v94
	v_mfma_f32_16x16x32_bf16 v[126:129], v[2:5], v[58:61], v[126:129]
	v_exp_f32_e32 v95, v95
	v_exp_f32_e32 v96, v96
	v_exp_f32_e32 v97, v97
	v_mfma_f32_16x16x32_bf16 v[2:5], v[2:5], v[42:45], v[122:125]
	v_exp_f32_e32 v38, v38
	v_exp_f32_e32 v39, v39
	v_exp_f32_e32 v40, v40
	v_mfma_f32_16x16x32_bf16 v[122:125], v[10:13], v[34:37], v[126:129]
	v_exp_f32_e32 v41, v41
	v_exp_f32_e32 v62, v62
	v_exp_f32_e32 v63, v63
	v_mfma_f32_16x16x32_bf16 v[126:129], v[10:13], v[18:21], v[2:5]
	ds_read_b64_tr_b16 v[2:3], v197 offset:0x2000
	ds_read_b64_tr_b16 v[4:5], v197 offset:0x3000
	s_waitcnt lgkmcnt(8)
	v_mfma_f32_16x16x32_bf16 v[130:133], v[138:141], v[18:21], v[130:133]
	v_cvt_pk_bf16_f32 v38, v38, v39
	v_cvt_pk_bf16_f32 v39, v40, v41
	v_cvt_pk_bf16_f32 v40, v62, v63
	v_mfma_f32_16x16x32_bf16 v[10:13], v[6:9], v[58:61], v[114:117]
	s_add_i32 s44, s44, s30
	s_add_i32 s43, s43, s30
	s_cmpk_gt_i32 s44, 0x1ff
	v_mfma_f32_16x16x32_bf16 v[6:9], v[6:9], v[42:45], v[118:121]
	v_mfma_f32_16x16x32_bf16 v[118:121], v[14:17], v[34:37], v[10:13]
	ds_read_b64_tr_b16 v[10:11], v198 offset:0
	ds_read_b64_tr_b16 v[12:13], v198 offset:0x1000
	v_mfma_f32_16x16x32_bf16 v[114:117], v[14:17], v[18:21], v[6:9]
	ds_read_b64_tr_b16 v[14:15], v198 offset:0x2000
	ds_read_b64_tr_b16 v[16:17], v198 offset:0x3000
	s_waitcnt lgkmcnt(8)
	s_nop 0
	v_mfma_f32_16x16x32_bf16 v[6:9], v[142:145], v[58:61], v[106:109]
	v_mfma_f32_16x16x32_bf16 v[106:109], v[142:145], v[42:45], v[110:113]
	ds_read_b64_tr_b16 v[142:143], v199 offset:0
	ds_read_b64_tr_b16 v[144:145], v199 offset:0x1000
	v_mfma_f32_16x16x32_bf16 v[110:113], v[146:149], v[34:37], v[6:9]
	v_mfma_f32_16x16x32_bf16 v[106:109], v[146:149], v[18:21], v[106:109]
	ds_read_b64_tr_b16 v[146:147], v199 offset:0x2000
	ds_read_b64_tr_b16 v[148:149], v199 offset:0x3000
	s_waitcnt lgkmcnt(8)
	s_nop 0
	v_mfma_f32_16x16x32_bf16 v[6:9], v[150:153], v[58:61], v[98:101]
	s_nop 2
	v_exp_f32_e32 v98, v76
	v_exp_f32_e32 v99, v77
	v_mfma_f32_16x16x32_bf16 v[74:77], v[150:153], v[42:45], v[102:105]
	v_exp_f32_e32 v100, v86
	v_exp_f32_e32 v101, v87
	ds_read_b64_tr_b16 v[86:87], v200 offset:0
	v_mfma_f32_16x16x32_bf16 v[6:9], v[2:5], v[34:37], v[6:9]
	v_exp_f32_e32 v102, v88
	v_exp_f32_e32 v103, v89
	ds_read_b64_tr_b16 v[88:89], v200 offset:0x1000
	v_mfma_f32_16x16x32_bf16 v[2:5], v[2:5], v[18:21], v[74:77]
	ds_read_b64_tr_b16 v[74:75], v200 offset:0x2000
	ds_read_b64_tr_b16 v[76:77], v200 offset:0x3000
	s_waitcnt lgkmcnt(8)
	v_exp_f32_e32 v104, v22
	v_mfma_f32_16x16x32_bf16 v[78:81], v[10:13], v[58:61], v[78:81]
	v_exp_f32_e32 v105, v23
	v_exp_f32_e32 v150, v24
	v_mfma_f32_16x16x32_bf16 v[82:85], v[10:13], v[42:45], v[82:85]
	v_mfma_f32_16x16x32_bf16 v[10:13], v[14:17], v[34:37], v[78:81]
	ds_read_b64_tr_b16 v[78:79], v201 offset:0
	ds_read_b64_tr_b16 v[80:81], v201 offset:0x1000
	v_mfma_f32_16x16x32_bf16 v[14:17], v[14:17], v[18:21], v[82:85]
	ds_read_b64_tr_b16 v[82:83], v201 offset:0x2000
	ds_read_b64_tr_b16 v[84:85], v201 offset:0x3000
	s_waitcnt lgkmcnt(8)
	s_waitcnt lgkmcnt(4)
	s_nop 0
	v_mfma_f32_16x16x32_bf16 v[66:69], v[142:145], v[58:61], v[66:69]
	s_waitcnt lgkmcnt(0)
	v_mfma_f32_16x16x32_bf16 v[54:57], v[86:89], v[58:61], v[54:57]
	v_mfma_f32_16x16x32_bf16 v[58:61], v[78:81], v[58:61], v[30:33]
	v_mfma_f32_16x16x32_bf16 v[70:73], v[142:145], v[42:45], v[70:73]
	v_exp_f32_e32 v142, v25
	v_exp_f32_e32 v143, v26
	v_exp_f32_e32 v144, v27
	v_mfma_f32_16x16x32_bf16 v[22:25], v[146:149], v[34:37], v[66:69]
	v_cvt_pk_bf16_f32 v30, v90, v91
	v_cvt_pk_bf16_f32 v31, v92, v93
	v_cvt_pk_bf16_f32 v32, v94, v95
	v_exp_f32_e32 v66, v28
	v_exp_f32_e32 v67, v29
	v_mfma_f32_16x16x32_bf16 v[50:53], v[86:89], v[42:45], v[50:53]
	v_exp_f32_e32 v68, v64
	v_exp_f32_e32 v69, v65
	v_cvt_pk_bf16_f32 v33, v96, v97
	v_mfma_f32_16x16x32_bf16 v[54:57], v[74:77], v[34:37], v[54:57]
	v_cvt_pk_bf16_f32 v41, v68, v69
	v_mfma_f32_16x16x32_bf16 v[42:45], v[78:81], v[42:45], v[46:49]
	v_mfma_f32_16x16x32_bf16 v[46:49], v[82:85], v[34:37], v[58:61]
	v_cvt_pk_bf16_f32 v34, v154, v161
	v_cvt_pk_bf16_f32 v35, v98, v99
	v_cvt_pk_bf16_f32 v36, v100, v101
	v_cvt_pk_bf16_f32 v37, v102, v103
	v_mfma_f32_16x16x32_bf16 v[62:65], v[74:77], v[18:21], v[50:53]
	v_lshlrev_b32_e32 v154, 1, v156
	v_mfma_f32_16x16x32_bf16 v[58:61], v[138:141], v[34:37], v[134:137]
	s_nop 0
	v_cvt_pk_bf16_f32 v50, v104, v105
	v_cvt_pk_bf16_f32 v51, v150, v142
	v_cvt_pk_bf16_f32 v52, v143, v144
	v_cvt_pk_bf16_f32 v53, v66, v67
	v_mfma_f32_16x16x32_bf16 v[58:61], v[138:141], v[30:33], v[58:61]
	s_nop 0
	v_mfma_f32_16x16x32_bf16 v[78:81], v[138:141], v[50:53], v[130:133]
	v_mfma_f32_16x16x32_bf16 v[78:81], v[138:141], v[38:41], v[78:81]
	s_nop 4
	v_div_scale_f32 v59, s[2:3], v58, v58, 1.0
	v_mfma_f32_16x16x32_bf16 v[26:29], v[146:149], v[18:21], v[70:73]
	v_mfma_f32_16x16x32_bf16 v[18:21], v[82:85], v[18:21], v[42:45]
	v_rcp_f32_e32 v79, v59
	ds_read_b64_tr_b16 v[42:43], v202 offset:0
	ds_read_b64_tr_b16 v[44:45], v202 offset:0x1000
	ds_read_b64_tr_b16 v[66:67], v202 offset:0x2000
	ds_read_b64_tr_b16 v[68:69], v202 offset:0x3000
	ds_read_b64_tr_b16 v[70:71], v203 offset:0
	ds_read_b64_tr_b16 v[72:73], v203 offset:0x1000
	ds_read_b64_tr_b16 v[74:75], v203 offset:0x2000
	ds_read_b64_tr_b16 v[76:77], v203 offset:0x3000
	ds_read_b64_tr_b16 v[82:83], v204 offset:0
	ds_read_b64_tr_b16 v[84:85], v204 offset:0x1000
	ds_read_b64_tr_b16 v[86:87], v204 offset:0x2000
	ds_read_b64_tr_b16 v[88:89], v204 offset:0x3000
	s_nop 0
	s_waitcnt lgkmcnt(8)
; #define AT_TR4(slot, d) do { const unsigned _a = vaddr + (unsigned)vo[d]; AT_TR(r[slot][0], _a, 0); AT_TR(r[slot][1], _a, 16 * 256); AT_TR(r[slot][2], _a, 32 * 256); AT_TR(r[slot][3], _a, 48 * 256); } while (0)
; #define AT_TR4(slot, d) do { const unsigned _a = vaddr + (unsigned)vo[d]; AT_TR(r[slot][0], _a, 0); AT_TR(r[slot][1], _a, 16 * 256); AT_TR(r[slot][2], _a, 32 * 256); AT_TR(r[slot][3], _a, 48 * 256); } while (0)
; __device__ __forceinline__ void attn_pv(unsigned vaddr, const int (&vo)[8], const bf16x8 (&pf)[2][2], f32x4 (&o)[2][8], f32x4 (&ol)[2]) {
;     s16x4 r[3][4];
;     ...
;     AT_TR4(0, 0); AT_TR4(1, 1);
;     { const bf16x8 ones = (bf16x8){0x3f80, 0x3f80, 0x3f80, 0x3f80, 0x3f80, 0x3f80, 0x3f80, 0x3f80};
; #pragma unroll
;       for (int c = 0; c < 2; ++c)
; #pragma unroll
;           for (int si = 0; si < 2; ++si) ol[c] = __builtin_amdgcn_mfma_f32_16x16x32_bf16(ones, pf[c][si], ol[c], 0, 0, 0); }
; #pragma unroll
;     for (int dt = 0; dt < 8; ++dt) {
;         const int cb = dt % 3;
;         if (dt < 6) { AT_TR4((dt + 2) % 3, dt + 2); asm volatile("s_waitcnt lgkmcnt(8)" : "+v"(r[cb][0]), "+v"(r[cb][1]), "+v"(r[cb][2]), "+v"(r[cb][3])); }
;         else if (dt == 6) asm volatile("s_waitcnt lgkmcnt(4)" : "+v"(r[cb][0]), "+v"(r[cb][1]), "+v"(r[cb][2]), "+v"(r[cb][3]));
;         else asm volatile("s_waitcnt lgkmcnt(0)" : "+v"(r[cb][0]), "+v"(r[cb][1]), "+v"(r[cb][2]), "+v"(r[cb][3]));
; #pragma unroll
;         for (int si = 0; si < 2; ++si) {
;             const s16x4 lo = r[cb][2 * si], hi = r[cb][2 * si + 1];
;             const bf16x8 vf = (bf16x8){lo[0], lo[1], lo[2], lo[3], hi[0], hi[1], hi[2], hi[3]};
;             o[0][dt] = __builtin_amdgcn_mfma_f32_16x16x32_bf16(vf, pf[0][si], o[0][dt], 0, 0, 0);
;             o[1][dt] = __builtin_amdgcn_mfma_f32_16x16x32_bf16(vf, pf[1][si], o[1][dt], 0, 0, 0);
;         }
;     }
;     ...
; }
; __device__ __forceinline__ void attn_unit(LAS unsigned char* lds, int seq, int h, int qb, bf16_t* UQ, const bf16_t* KB, const bf16_t* VB, const float* rel_bias, const float* subln, float lam, float bmax) {
;     ...
;     const float i0 = 1.0f / ol[0][0], i1 = lam / ol[1][0];
;     float ss = 0.f;
; #pragma unroll
;     for (int dt = 0; dt < 8; ++dt)
; #pragma unroll
;         for (int j = 0; j < 4; ++j) { const float v = o[0][dt][j] * i0 - o[1][dt][j] * i1; o[0][dt][j] = v; ss += v * v; }
	ds_read_b64_tr_b16 v[90:91], v205 offset:0
	ds_read_b64_tr_b16 v[92:93], v205 offset:0x1000
	ds_read_b64_tr_b16 v[98:99], v205 offset:0x2000
	ds_read_b64_tr_b16 v[100:101], v205 offset:0x3000
	s_waitcnt lgkmcnt(8)
	s_nop 0
	v_mfma_f32_16x16x32_bf16 v[94:97], v[42:45], v[34:37], v[122:125]
	v_fma_f32 v60, -v59, v79, 1.0
	ds_read_b64_tr_b16 v[102:103], v206 offset:0
	ds_read_b64_tr_b16 v[104:105], v206 offset:0x1000
	v_mfma_f32_16x16x32_bf16 v[42:45], v[42:45], v[50:53], v[126:129]
	ds_read_b64_tr_b16 v[122:123], v206 offset:0x2000
	ds_read_b64_tr_b16 v[124:125], v206 offset:0x3000
	s_waitcnt lgkmcnt(8)
	v_mfma_f32_16x16x32_bf16 v[118:121], v[70:73], v[34:37], v[118:121]
	v_fmac_f32_e32 v79, v60, v79
	v_div_scale_f32 v60, vcc, 1.0, v58, 1.0
	v_mfma_f32_16x16x32_bf16 v[70:73], v[70:73], v[50:53], v[114:117]
	v_mfma_f32_16x16x32_bf16 v[110:113], v[82:85], v[34:37], v[110:113]
	v_mfma_f32_16x16x32_bf16 v[80:83], v[82:85], v[50:53], v[106:109]
	v_mul_f32_e32 v84, v60, v79
	v_fma_f32 v61, -v59, v84, v60
	v_fmac_f32_e32 v84, v61, v79
	v_mfma_f32_16x16x32_bf16 v[94:97], v[66:69], v[30:33], v[94:97]
	v_fma_f32 v59, -v59, v84, v60
	v_div_fmas_f32 v59, v59, v79, v84
	v_mfma_f32_16x16x32_bf16 v[42:45], v[66:69], v[38:41], v[42:45]
	ds_read_b64_tr_b16 v[66:67], v207 offset:0
	ds_read_b64_tr_b16 v[68:69], v207 offset:0x1000
	ds_read_b64_tr_b16 v[126:127], v207 offset:0x2000
	ds_read_b64_tr_b16 v[128:129], v207 offset:0x3000
	s_waitcnt lgkmcnt(8)
	ds_read_b64_tr_b16 v[130:131], v208 offset:0
	ds_read_b64_tr_b16 v[132:133], v208 offset:0x1000
	ds_read_b64_tr_b16 v[114:115], v208 offset:0x2000
	ds_read_b64_tr_b16 v[116:117], v208 offset:0x3000
	v_mfma_f32_16x16x32_bf16 v[118:121], v[74:77], v[30:33], v[118:121]
	s_waitcnt lgkmcnt(8)
	ds_read_b64_tr_b16 v[134:135], v209 offset:0
	ds_read_b64_tr_b16 v[136:137], v209 offset:0x1000
	v_mfma_f32_16x16x32_bf16 v[70:73], v[74:77], v[38:41], v[70:73]
	ds_read_b64_tr_b16 v[74:75], v209 offset:0x2000
	ds_read_b64_tr_b16 v[76:77], v209 offset:0x3000
	s_waitcnt lgkmcnt(8)
	s_waitcnt lgkmcnt(4)
	v_mfma_f32_16x16x32_bf16 v[2:5], v[90:93], v[50:53], v[2:5]
	s_waitcnt lgkmcnt(0)
	v_mfma_f32_16x16x32_bf16 v[60:63], v[130:133], v[50:53], v[62:65]
	s_nop 2
	v_div_scale_f32 v65, s[2:3], v78, v78, v174
	v_rcp_f32_e32 v85, v65
	v_mfma_f32_16x16x32_bf16 v[18:21], v[134:137], v[50:53], v[18:21]
	v_div_fixup_f32 v64, v59, v58, 1.0
	v_fma_f32 v79, -v65, v85, 1.0
	v_mfma_f32_16x16x32_bf16 v[58:61], v[114:117], v[38:41], v[60:63]
	v_fmac_f32_e32 v85, v79, v85
	s_nop 1
	v_div_scale_f32 v62, vcc, v174, v78, v174
	v_mfma_f32_16x16x32_bf16 v[46:49], v[134:137], v[34:37], v[46:49]
	v_mul_f32_e32 v63, v62, v85
	v_fma_f32 v79, -v65, v63, v62
	v_fmac_f32_e32 v63, v79, v85
	v_mfma_f32_16x16x32_bf16 v[18:21], v[74:77], v[38:41], v[18:21]
	v_fma_f32 v62, -v65, v63, v62
	v_div_fmas_f32 v62, v62, v85, v63
	v_div_fixup_f32 v78, v62, v78, v174
	v_mfma_f32_16x16x32_bf16 v[46:49], v[74:77], v[30:33], v[46:49]
	v_mul_f32_e64 v42, v78, v42
	v_mul_f32_e64 v43, v78, v43
	s_nop 1
	v_pk_mul_f32 v[18:19], v[78:79], v[18:19] op_sel_hi:[0,1]
	v_pk_fma_f32 v[42:43], v[64:65], v[94:95], v[42:43] op_sel_hi:[0,1,1] neg_lo:[0,0,1] neg_hi:[0,0,1]
	v_mfma_f32_16x16x32_bf16 v[6:9], v[90:93], v[34:37], v[6:9]
	v_mul_f32_e64 v44, v78, v44
	v_mul_f32_e64 v45, v78, v45
	v_pk_fma_f32 v[46:47], v[64:65], v[46:47], v[18:19] op_sel_hi:[0,1,1] neg_lo:[0,0,1] neg_hi:[0,0,1]
	v_pk_mul_f32 v[18:19], v[78:79], v[20:21] op_sel_hi:[0,1]
	v_pk_fma_f32 v[48:49], v[64:65], v[48:49], v[18:19] op_sel_hi:[0,1,1] neg_lo:[0,0,1] neg_hi:[0,0,1]
	global_load_dwordx4 v[18:21], v[158:159], off
	v_mfma_f32_16x16x32_bf16 v[2:5], v[98:101], v[38:41], v[2:5]
	v_mul_f32_e64 v60, v78, v60
	v_mul_f32_e64 v61, v78, v61
	v_pk_fma_f32 v[44:45], v[64:65], v[96:97], v[44:45] op_sel_hi:[0,1,1] neg_lo:[0,0,1] neg_hi:[0,0,1]
	v_pk_mul_f32 v[84:85], v[42:43], v[42:43]
	v_mfma_f32_16x16x32_bf16 v[54:57], v[130:133], v[34:37], v[54:57]
	v_mul_f32_e64 v70, v78, v70
	v_mul_f32_e64 v71, v78, v71
	s_nop 0
	v_pk_mul_f32 v[4:5], v[78:79], v[4:5] op_sel_hi:[0,1]
	v_pk_fma_f32 v[70:71], v[64:65], v[118:119], v[70:71] op_sel_hi:[0,1,1] neg_lo:[0,0,1] neg_hi:[0,0,1]
	v_mfma_f32_16x16x32_bf16 v[6:9], v[98:101], v[30:33], v[6:9]
	v_mul_f32_e64 v72, v78, v72
	v_mul_f32_e64 v73, v78, v73
	v_pk_fma_f32 v[72:73], v[64:65], v[120:121], v[72:73] op_sel_hi:[0,1,1] neg_lo:[0,0,1] neg_hi:[0,0,1]
	v_pk_mul_f32 v[76:77], v[46:47], v[46:47]
	v_mfma_f32_16x16x32_bf16 v[54:57], v[114:117], v[30:33], v[54:57]
	v_mfma_f32_16x16x32_bf16 v[10:13], v[102:105], v[34:37], v[10:13]
	s_nop 1
	v_fma_f32 v94, v64, v8, -v4
	v_fma_f32 v95, v64, v9, -v5
	v_pk_mul_f32 v[8:9], v[78:79], v[2:3] op_sel_hi:[0,1]
	s_nop 1
	v_pk_fma_f32 v[56:57], v[64:65], v[56:57], v[60:61] op_sel_hi:[0,1,1] neg_lo:[0,0,1] neg_hi:[0,0,1]
	v_mfma_f32_16x16x32_bf16 v[2:5], v[66:69], v[34:37], v[22:25]
	v_mul_f32_e64 v96, v94, v94
	v_mul_f32_e64 v97, v95, v95
	v_pk_mul_f32 v[74:75], v[56:57], v[56:57]
	v_mfma_f32_16x16x32_bf16 v[106:109], v[86:89], v[30:33], v[110:113]
	v_fma_f32 v22, v64, v6, -v8
	v_fma_f32 v23, v64, v7, -v9
	v_pk_mul_f32 v[24:25], v[22:23], v[22:23]
	v_mfma_f32_16x16x32_bf16 v[60:63], v[86:89], v[38:41], v[80:83]
	v_mul_f32_e64 v88, v70, v70
	v_mul_f32_e64 v89, v71, v71
	v_pk_mul_f32 v[86:87], v[72:73], v[72:73]
	v_pk_mul_f32 v[82:83], v[44:45], v[44:45]
	v_mfma_f32_16x16x32_bf16 v[10:13], v[122:125], v[30:33], v[10:13]
	s_nop 2
	v_mul_f32_e64 v60, v78, v60
	v_mul_f32_e64 v61, v78, v61
	v_pk_fma_f32 v[60:61], v[64:65], v[106:107], v[60:61] op_sel_hi:[0,1,1] neg_lo:[0,0,1] neg_hi:[0,0,1]
	v_pk_mul_f32 v[62:63], v[78:79], v[62:63] op_sel_hi:[0,1]
; __device__ __forceinline__ unsigned cvtpk(float lo, float hi) { f32x2 v = {lo, hi}; bf16x2_t b = __builtin_convertvector(v, bf16x2_t); return __builtin_bit_cast(unsigned, b); }
; #define AT_BAR(N) asm volatile("s_waitcnt vmcnt(" #N ") lgkmcnt(0)\n\ts_barrier" ::: "memory")
; __device__ __forceinline__ void attn_unit(LAS unsigned char* lds, int seq, int h, int qb, bf16_t* UQ, const bf16_t* KB, const bf16_t* VB, const float* rel_bias, const float* subln, float lam, float bmax) {
;     ...
;     const float i0 = 1.0f / ol[0][0], i1 = lam / ol[1][0];
;     float ss = 0.f;
; #pragma unroll
;     for (int dt = 0; dt < 8; ++dt)
; #pragma unroll
;         for (int j = 0; j < 4; ++j) { const float v = o[0][dt][j] * i0 - o[1][dt][j] * i1; o[0][dt][j] = v; ss += v * v; }
;     ss += __shfl_xor(ss, 16); ss += __shfl_xor(ss, 32);
;     const float rs = __builtin_amdgcn_rsqf(ss * (1.0f / 128.0f) + EPS) * 0.8f;
;     bf16_t* op = UQ + (size_t)(row0 + q0 + 16 * w + r16) * DM + 512 + 128 * h + 4 * fq;
; #pragma unroll
;     for (int dt = 0; dt < 8; ++dt) {
;         const f32x4 gsl = *(const f32x4*)(subln + 16 * dt + 4 * fq);
;         u32x2 wv; wv.x = cvtpk(o[0][dt][0] * rs * gsl[0], o[0][dt][1] * rs * gsl[1]); wv.y = cvtpk(o[0][dt][2] * rs * gsl[2], o[0][dt][3] * rs * gsl[3]);
;         *(u32x2*)(op + 16 * dt) = wv;
;     }
;     AT_BAR(0);
	v_mfma_f32_16x16x32_bf16 v[2:5], v[126:129], v[30:33], v[2:5]
	v_add_f32_e32 v30, v84, v85
	v_add_f32_e32 v30, v82, v30
	v_add_f32_e32 v30, v83, v30
	v_add_f32_e32 v30, v30, v88
	v_mfma_f32_16x16x32_bf16 v[14:17], v[102:105], v[50:53], v[14:17]
	v_add_f32_e32 v30, v89, v30
	v_add_f32_e32 v30, v86, v30
	v_pk_mul_f32 v[92:93], v[60:61], v[60:61]
	v_add_f32_e32 v30, v87, v30
	v_pk_fma_f32 v[62:63], v[64:65], v[108:109], v[62:63] op_sel_hi:[0,1,1] neg_lo:[0,0,1] neg_hi:[0,0,1]
	v_add_f32_e32 v30, v30, v92
	v_pk_mul_f32 v[90:91], v[62:63], v[62:63]
	v_mfma_f32_16x16x32_bf16 v[14:17], v[122:125], v[38:41], v[14:17]
	v_add_f32_e32 v30, v93, v30
	v_add_f32_e32 v30, v90, v30
	v_add_f32_e32 v30, v91, v30
	v_mfma_f32_16x16x32_bf16 v[6:9], v[66:69], v[50:53], v[26:29]
	v_add_f32_e32 v24, v30, v24
	s_nop 2
	v_pk_mul_f32 v[14:15], v[78:79], v[14:15] op_sel_hi:[0,1]
	v_add_f32_e32 v24, v25, v24
	v_mfma_f32_16x16x32_bf16 v[6:9], v[126:129], v[38:41], v[6:9]
	v_fma_f32 v10, v64, v10, -v14
	v_fma_f32 v11, v64, v11, -v15
	v_add_f32_e32 v24, v96, v24
	v_pk_mul_f32 v[16:17], v[78:79], v[16:17] op_sel_hi:[0,1]
	v_pk_mul_f32 v[14:15], v[10:11], v[10:11]
	v_add_f32_e32 v24, v97, v24
	v_pk_fma_f32 v[12:13], v[64:65], v[12:13], v[16:17] op_sel_hi:[0,1,1] neg_lo:[0,0,1] neg_hi:[0,0,1]
	v_add_f32_e32 v14, v24, v14
	v_pk_mul_f32 v[16:17], v[12:13], v[12:13]
	v_pk_mul_f32 v[6:7], v[78:79], v[6:7] op_sel_hi:[0,1]
	v_add_f32_e32 v14, v15, v14
	v_pk_fma_f32 v[6:7], v[64:65], v[2:3], v[6:7] op_sel_hi:[0,1,1] neg_lo:[0,0,1] neg_hi:[0,0,1]
	v_add_f32_e32 v14, v16, v14
	v_pk_mul_f32 v[8:9], v[78:79], v[8:9] op_sel_hi:[0,1]
	v_pk_mul_f32 v[2:3], v[6:7], v[6:7]
	v_add_f32_e32 v14, v17, v14
	v_pk_fma_f32 v[8:9], v[64:65], v[4:5], v[8:9] op_sel_hi:[0,1,1] neg_lo:[0,0,1] neg_hi:[0,0,1]
	v_add_f32_e32 v2, v14, v2
	v_pk_mul_f32 v[4:5], v[8:9], v[8:9]
	v_pk_mul_f32 v[26:27], v[78:79], v[58:59] op_sel_hi:[0,1]
	v_add_f32_e32 v2, v3, v2
	v_pk_fma_f32 v[26:27], v[64:65], v[54:55], v[26:27] op_sel_hi:[0,1,1] neg_lo:[0,0,1] neg_hi:[0,0,1]
	v_add_f32_e32 v2, v4, v2
	v_pk_mul_f32 v[28:29], v[26:27], v[26:27]
	v_add_f32_e32 v2, v5, v2
	v_add_f32_e32 v2, v2, v28
	v_add_f32_e32 v2, v29, v2
	v_add_f32_e32 v2, v74, v2
	v_add_f32_e32 v2, v75, v2
	v_add_f32_e32 v2, v2, v76
	v_pk_mul_f32 v[80:81], v[48:49], v[48:49]
	v_add_f32_e32 v2, v77, v2
	v_add_f32_e32 v2, v80, v2
	v_add_f32_e32 v2, v81, v2
	ds_bpermute_b32 v3, v1, v2
	v_lshl_add_u64 v[14:15], v[162:163], 0, v[154:155]
	s_waitcnt lgkmcnt(0)
	v_add_f32_e32 v2, v2, v3
	ds_bpermute_b32 v3, v157, v2
	s_waitcnt lgkmcnt(0)
	v_add_f32_e32 v2, v2, v3
	v_fmamk_f32 v2, v2, 0x3c000000, v211
	v_rsq_f32_e32 v2, v2
	s_nop 0
	v_mul_f32_e32 v16, 0x3f4ccccd, v2
	v_pk_mul_f32 v[2:3], v[42:43], v[16:17] op_sel_hi:[1,0]
	v_pk_mul_f32 v[4:5], v[44:45], v[16:17] op_sel_hi:[1,0]
	s_waitcnt vmcnt(0)
	v_pk_mul_f32 v[2:3], v[18:19], v[2:3]
	v_pk_mul_f32 v[4:5], v[20:21], v[4:5]
	v_cvt_pk_bf16_f32 v2, v2, v3
	v_cvt_pk_bf16_f32 v3, v4, v5
	global_store_dwordx2 v[14:15], v[2:3], off offset:1024
	global_load_dwordx4 v[216:219], v[158:159], off offset:64
	global_load_dwordx4 v[220:223], v[158:159], off offset:128
	global_load_dwordx4 v[224:227], v[158:159], off offset:192
	global_load_dwordx4 v[228:231], v[158:159], off offset:256
	global_load_dwordx4 v[232:235], v[158:159], off offset:320
	global_load_dwordx4 v[236:239], v[158:159], off offset:384
	global_load_dwordx4 v[240:243], v[158:159], off offset:448
	v_pk_mul_f32 v[18:19], v[70:71], v[16:17] op_sel_hi:[1,0]
	v_pk_mul_f32 v[20:21], v[94:95], v[16:17] op_sel_hi:[1,0]
	v_pk_mul_f32 v[10:11], v[10:11], v[16:17] op_sel_hi:[1,0]
	v_pk_mul_f32 v[12:13], v[12:13], v[16:17] op_sel_hi:[1,0]
	v_pk_mul_f32 v[6:7], v[6:7], v[16:17] op_sel_hi:[1,0]
	v_pk_mul_f32 v[8:9], v[8:9], v[16:17] op_sel_hi:[1,0]
	s_waitcnt vmcnt(6)
	v_pk_mul_f32 v[2:3], v[216:217], v[18:19]
	v_pk_mul_f32 v[18:19], v[72:73], v[16:17] op_sel_hi:[1,0]
	v_cvt_pk_bf16_f32 v2, v2, v3
	v_pk_mul_f32 v[4:5], v[218:219], v[18:19]
	v_pk_mul_f32 v[18:19], v[60:61], v[16:17] op_sel_hi:[1,0]
	v_cvt_pk_bf16_f32 v3, v4, v5
	global_store_dwordx2 v[14:15], v[2:3], off offset:1056
	s_waitcnt vmcnt(6)
	v_pk_mul_f32 v[2:3], v[220:221], v[18:19]
	v_pk_mul_f32 v[18:19], v[62:63], v[16:17] op_sel_hi:[1,0]
	v_cvt_pk_bf16_f32 v2, v2, v3
	v_pk_mul_f32 v[4:5], v[222:223], v[18:19]
	v_pk_mul_f32 v[18:19], v[22:23], v[16:17] op_sel_hi:[1,0]
	v_cvt_pk_bf16_f32 v3, v4, v5
	global_store_dwordx2 v[14:15], v[2:3], off offset:1088
	s_waitcnt vmcnt(6)
	v_pk_mul_f32 v[2:3], v[224:225], v[18:19]
	v_pk_mul_f32 v[4:5], v[226:227], v[20:21]
	v_cvt_pk_bf16_f32 v2, v2, v3
	v_cvt_pk_bf16_f32 v3, v4, v5
	global_store_dwordx2 v[14:15], v[2:3], off offset:1120
	s_waitcnt vmcnt(6)
	v_pk_mul_f32 v[2:3], v[228:229], v[10:11]
	v_pk_mul_f32 v[4:5], v[230:231], v[12:13]
	v_cvt_pk_bf16_f32 v2, v2, v3
	v_cvt_pk_bf16_f32 v3, v4, v5
	global_store_dwordx2 v[14:15], v[2:3], off offset:1152
	s_waitcnt vmcnt(6)
	v_pk_mul_f32 v[2:3], v[232:233], v[6:7]
	v_pk_mul_f32 v[4:5], v[234:235], v[8:9]
	v_cvt_pk_bf16_f32 v2, v2, v3
	v_cvt_pk_bf16_f32 v3, v4, v5
	global_store_dwordx2 v[14:15], v[2:3], off offset:1184
	v_pk_mul_f32 v[6:7], v[26:27], v[16:17] op_sel_hi:[1,0]
	v_pk_mul_f32 v[8:9], v[56:57], v[16:17] op_sel_hi:[1,0]
	s_waitcnt vmcnt(6)
	v_pk_mul_f32 v[2:3], v[236:237], v[6:7]
	v_pk_mul_f32 v[4:5], v[238:239], v[8:9]
	v_cvt_pk_bf16_f32 v2, v2, v3
	v_cvt_pk_bf16_f32 v3, v4, v5
	global_store_dwordx2 v[14:15], v[2:3], off offset:1216
	v_pk_mul_f32 v[6:7], v[46:47], v[16:17] op_sel_hi:[1,0]
	v_pk_mul_f32 v[8:9], v[48:49], v[16:17] op_sel_hi:[1,0]
	s_waitcnt vmcnt(6)
	v_pk_mul_f32 v[2:3], v[6:7], v[240:241]
	v_pk_mul_f32 v[4:5], v[8:9], v[242:243]
	v_cvt_pk_bf16_f32 v2, v2, v3
	v_cvt_pk_bf16_f32 v3, v4, v5
	global_store_dwordx2 v[14:15], v[2:3], off offset:1248
	s_waitcnt vmcnt(0) lgkmcnt(0)
	s_barrier
	s_cbranch_scc1 .LBB0_520

; #define LAS __attribute__((address_space(3)))
; __device__ __forceinline__ unsigned cvtpk(float lo, float hi) { f32x2 v = {lo, hi}; bf16x2_t b = __builtin_convertvector(v, bf16x2_t); return __builtin_bit_cast(unsigned, b); }
; __device__ __forceinline__ float fast_exp2(float x) { return __builtin_amdgcn_exp2f(x); }
; #define AT_BAR(N) asm volatile("s_waitcnt vmcnt(" #N ") lgkmcnt(0)\n\ts_barrier" ::: "memory")
; template <bool QK, bool PV> ...
;     ...
;         {
;             const int c = dt >> 2, kt = dt & 3;
; #pragma unroll
;             for (int j = 0; j < 4; ++j) s[c][kt][j] = fast_exp2(s[c][kt][j]);
;             if (kt & 1) { const int si = kt >> 1;
;                 u32x4 wv; wv.x = cvtpk(s[c][2 * si][0], s[c][2 * si][1]); wv.y = cvtpk(s[c][2 * si][2], s[c][2 * si][3]);
;                 wv.z = cvtpk(s[c][2 * si + 1][0], s[c][2 * si + 1][1]); wv.w = cvtpk(s[c][2 * si + 1][2], s[c][2 * si + 1][3]);
;                 pn[c][si] = __builtin_bit_cast(bf16x8, wv); }
;         }
;     }
;     ...
; #pragma unroll
;     for (int c = 0; c < 2; ++c)
; #pragma unroll
;         for (int si = 0; si < 2; ++si) pf[c][si] = pn[c][si];
;     if constexpr (QK) {
; #pragma unroll
;         for (int kt = 0; kt < 4; ++kt)
; #pragma unroll
;             for (int c = 0; c < 2; ++c) {
;                 f32x4 a = tbv[kt];
; #pragma unroll
;                 for (int kk = 0; kk < 2; ++kk) { const bf16x8 kf = *(const LAS bf16x8*)(kbuf + kfo[c][kk] + kt * 4096); a = __builtin_amdgcn_mfma_f32_16x16x32_bf16(kf, qf[c][kk], a, 0, 0, 0); }
;                 s[c][kt] = a;
;             }
;     }
; __device__ __forceinline__ void attn_unit(LAS unsigned char* lds, int seq, int h, int qb, bf16_t* UQ, const bf16_t* KB, const bf16_t* VB, const float* rel_bias, const float* subln, float lam, float bmax) {
;     ...
;     attn_step<true, false>(lds + AT_K0 + AT_TILE, 0u, kfo, vo, qf, s, pf, o, ol, tbv);
;     AT_BAR(4);
;     int k_i = AT_K0 + AT_TILE, k_n = AT_K0 + 2 * AT_TILE, k_p = AT_K0;
.LBB0_513:
	v_exp_f32_e32 v82, v42
	v_exp_f32_e32 v83, v43
	v_exp_f32_e32 v84, v44
	v_exp_f32_e32 v85, v45
	ds_read_b128 v[42:45], v67 offset:16384
	v_exp_f32_e32 v94, v22
	v_exp_f32_e32 v95, v23
	v_exp_f32_e32 v96, v24
	v_exp_f32_e32 v97, v25
	ds_read_b128 v[22:25], v69 offset:16384
	v_exp_f32_e32 v98, v46
	v_exp_f32_e32 v99, v47
	v_exp_f32_e32 v100, v48
	v_exp_f32_e32 v101, v49
	ds_read_b128 v[46:49], v66 offset:16384
	ds_read_b128 v[70:73], v67 offset:20480
	s_waitcnt lgkmcnt(0)
	v_mfma_f32_16x16x32_bf16 v[42:45], v[42:45], v[2:5], v[58:61]
	v_exp_f32_e32 v102, v38
	v_exp_f32_e32 v103, v39
	v_exp_f32_e32 v104, v40
	v_exp_f32_e32 v105, v41
	ds_read_b128 v[38:41], v68 offset:16384
	ds_read_b128 v[78:81], v69 offset:20480
	v_mfma_f32_16x16x32_bf16 v[74:77], v[22:25], v[6:9], v[42:45]
	v_exp_f32_e32 v106, v18
	v_exp_f32_e32 v107, v19
	v_exp_f32_e32 v108, v28
	ds_read_b128 v[42:45], v66 offset:20480
	v_mfma_f32_16x16x32_bf16 v[22:25], v[46:49], v[10:13], v[58:61]
	v_exp_f32_e32 v109, v29
	s_and_b32 s2, s43, 31
	s_lshl_b32 s52, s2, 1
	v_exp_f32_e32 v58, v20
	v_exp_f32_e32 v59, v21
	ds_read_b128 v[18:21], v68 offset:20480
	s_waitcnt lgkmcnt(0)
	v_mfma_f32_16x16x32_bf16 v[22:25], v[38:41], v[14:17], v[22:25]
	v_exp_f32_e32 v60, v26
	v_exp_f32_e32 v61, v27
	s_add_i32 s52, s52, 2
	v_mfma_f32_16x16x32_bf16 v[38:41], v[70:73], v[2:5], v[50:53]
	v_exp_f32_e32 v70, v30
	v_exp_f32_e32 v71, v31
	v_exp_f32_e32 v72, v32
	v_exp_f32_e32 v73, v33
	ds_read_b128 v[30:33], v67 offset:24576
	v_mfma_f32_16x16x32_bf16 v[86:89], v[78:81], v[6:9], v[38:41]
	v_exp_f32_e32 v78, v34
	v_exp_f32_e32 v79, v35
	v_exp_f32_e32 v80, v36
	ds_read_b128 v[38:41], v69 offset:24576
	v_mfma_f32_16x16x32_bf16 v[26:29], v[42:45], v[10:13], v[50:53]
	ds_read_b128 v[42:45], v66 offset:24576
	ds_read_b128 v[46:49], v67 offset:28672
	v_exp_f32_e32 v67, v37
	s_addk_i32 s53, 0xff42
	v_mfma_f32_16x16x32_bf16 v[26:29], v[18:21], v[14:17], v[26:29]
	s_add_i32 s54, s45, -1
	s_movk_i32 s59, 0x4000
	s_mov_b32 s58, 0x8000
	s_waitcnt lgkmcnt(0)
	v_mfma_f32_16x16x32_bf16 v[18:21], v[30:33], v[2:5], v[62:65]
	ds_read_b128 v[30:33], v68 offset:24576
	ds_read_b128 v[50:53], v69 offset:28672
	s_mov_b32 s55, 0x10000
	s_mov_b32 s60, 0
	v_mfma_f32_16x16x32_bf16 v[90:93], v[38:41], v[6:9], v[18:21]
	s_mov_b32 s2, 0
	s_nop 1
	v_cvt_pk_bf16_f32 v18, v70, v71
	v_cvt_pk_bf16_f32 v19, v72, v73
	ds_read_b128 v[70:73], v66 offset:28672
	v_mfma_f32_16x16x32_bf16 v[34:37], v[42:45], v[10:13], v[62:65]
	v_cvt_pk_bf16_f32 v20, v78, v79
	v_cvt_pk_bf16_f32 v21, v80, v67
	v_cvt_pk_bf16_f32 v42, v106, v107
	ds_read_b128 v[62:65], v68 offset:28672
	s_waitcnt lgkmcnt(0)
	v_mfma_f32_16x16x32_bf16 v[38:41], v[30:33], v[14:17], v[34:37]
	s_waitcnt vmcnt(4) lgkmcnt(0)
	s_barrier
	v_cvt_pk_bf16_f32 v43, v58, v59
	v_cvt_pk_bf16_f32 v44, v60, v61
	v_mfma_f32_16x16x32_bf16 v[30:33], v[46:49], v[2:5], v[54:57]
	v_cvt_pk_bf16_f32 v34, v94, v95
	v_cvt_pk_bf16_f32 v35, v96, v97
	v_cvt_pk_bf16_f32 v45, v108, v109
	v_mfma_f32_16x16x32_bf16 v[94:97], v[50:53], v[6:9], v[30:33]
	v_cvt_pk_bf16_f32 v36, v102, v103
	v_cvt_pk_bf16_f32 v37, v104, v105
	v_cvt_pk_bf16_f32 v58, v82, v83
	v_mfma_f32_16x16x32_bf16 v[30:33], v[70:73], v[10:13], v[54:57]
	v_cvt_pk_bf16_f32 v59, v84, v85
	v_cvt_pk_bf16_f32 v60, v98, v99
	v_cvt_pk_bf16_f32 v61, v100, v101
	v_mfma_f32_16x16x32_bf16 v[62:65], v[62:65], v[14:17], v[30:33]
	s_nop 3
	v_mov_b32_e32 v30, 0
	v_mov_b32_e32 v31, v30
	v_mov_b32_e32 v32, v30
	v_mov_b32_e32 v33, v30
	v_mov_b32_e32 v46, v30
	v_mov_b32_e32 v47, v30
	v_mov_b32_e32 v48, v30
	v_mov_b32_e32 v49, v30
	v_mov_b32_e32 v54, v30
	v_mov_b32_e32 v55, v30
	v_mov_b32_e32 v56, v30
	v_mov_b32_e32 v57, v30
	v_mov_b32_e32 v50, v30
	v_mov_b32_e32 v51, v30
	v_mov_b32_e32 v52, v30
	v_mov_b32_e32 v53, v30
	v_mov_b32_e32 v66, v30
	v_mov_b32_e32 v67, v30
	v_mov_b32_e32 v68, v30
	v_mov_b32_e32 v69, v30
	v_mov_b32_e32 v70, v30
	v_mov_b32_e32 v71, v30
	v_mov_b32_e32 v72, v30
	v_mov_b32_e32 v73, v30
	v_mov_b32_e32 v78, v30
	v_mov_b32_e32 v79, v30
	v_mov_b32_e32 v80, v30
	v_mov_b32_e32 v81, v30
	v_mov_b32_e32 v82, v30
	v_mov_b32_e32 v83, v30
	v_mov_b32_e32 v84, v30
	v_mov_b32_e32 v85, v30
	v_mov_b32_e32 v98, v30
	v_mov_b32_e32 v99, v30
	v_mov_b32_e32 v100, v30
	v_mov_b32_e32 v101, v30
	v_mov_b32_e32 v102, v30
	v_mov_b32_e32 v103, v30
	v_mov_b32_e32 v104, v30
	v_mov_b32_e32 v105, v30
	v_mov_b32_e32 v106, v30
	v_mov_b32_e32 v107, v30
	v_mov_b32_e32 v108, v30
	v_mov_b32_e32 v109, v30
	v_mov_b32_e32 v110, v30
	v_mov_b32_e32 v111, v30
	v_mov_b32_e32 v112, v30
	v_mov_b32_e32 v113, v30
	v_mov_b32_e32 v114, v30
	v_mov_b32_e32 v115, v30
	v_mov_b32_e32 v116, v30
	v_mov_b32_e32 v117, v30
	v_mov_b32_e32 v118, v30
	v_mov_b32_e32 v119, v30
	v_mov_b32_e32 v120, v30
	v_mov_b32_e32 v121, v30
	v_mov_b32_e32 v122, v30
	v_mov_b32_e32 v123, v30
	v_mov_b32_e32 v124, v30
	v_mov_b32_e32 v125, v30
	v_mov_b32_e32 v134, v30
	v_mov_b32_e32 v135, v30
	v_mov_b32_e32 v136, v30
	v_mov_b32_e32 v137, v30
	v_mov_b32_e32 v130, v30
	v_mov_b32_e32 v131, v30
	v_mov_b32_e32 v132, v30
	v_mov_b32_e32 v133, v30
	v_mov_b32_e32 v126, v30
	v_mov_b32_e32 v127, v30
	v_mov_b32_e32 v128, v30
	v_mov_b32_e32 v129, v30
	v_readfirstlane_b32 s98, v171
	s_nop 3
	s_lshr_b32 s98, s98, 6
	s_cmp_lt_u32 s98, 4
	s_cbranch_scc1 .Lat_xskip_s
	s_setprio 1
	s_barrier

; __device__ __forceinline__ void attn_pv(unsigned vaddr, const int (&vo)[8], const bf16x8 (&pf)[2][2], f32x4 (&o)[2][8], f32x4 (&ol)[2]) {
;     s16x4 r[3][4];
;     ...
;     AT_TR4(0, 0); AT_TR4(1, 1);
;     { const bf16x8 ones = (bf16x8){0x3f80, 0x3f80, 0x3f80, 0x3f80, 0x3f80, 0x3f80, 0x3f80, 0x3f80};
; #pragma unroll
;       for (int c = 0; c < 2; ++c)
; #pragma unroll
;           for (int si = 0; si < 2; ++si) ol[c] = __builtin_amdgcn_mfma_f32_16x16x32_bf16(ones, pf[c][si], ol[c], 0, 0, 0); }
; #pragma unroll
;     for (int dt = 0; dt < 8; ++dt) {
;         const int cb = dt % 3;
;         if (dt < 6) { AT_TR4((dt + 2) % 3, dt + 2); asm volatile("s_waitcnt lgkmcnt(8)" : "+v"(r[cb][0]), "+v"(r[cb][1]), "+v"(r[cb][2]), "+v"(r[cb][3])); }
;         else if (dt == 6) asm volatile("s_waitcnt lgkmcnt(4)" : "+v"(r[cb][0]), "+v"(r[cb][1]), "+v"(r[cb][2]), "+v"(r[cb][3]));
;         else asm volatile("s_waitcnt lgkmcnt(0)" : "+v"(r[cb][0]), "+v"(r[cb][1]), "+v"(r[cb][2]), "+v"(r[cb][3]));
; #pragma unroll
;         for (int si = 0; si < 2; ++si) {
;             const s16x4 lo = r[cb][2 * si], hi = r[cb][2 * si + 1];
;             const bf16x8 vf = (bf16x8){lo[0], lo[1], lo[2], lo[3], hi[0], hi[1], hi[2], hi[3]};
;             o[0][dt] = __builtin_amdgcn_mfma_f32_16x16x32_bf16(vf, pf[0][si], o[0][dt], 0, 0, 0);
;             o[1][dt] = __builtin_amdgcn_mfma_f32_16x16x32_bf16(vf, pf[1][si], o[1][dt], 0, 0, 0);
;         }
;     }
;     ...
; }
; template <bool QK, bool PV> ...
;     ...
;     if constexpr (PV) { AT_TR4(0, 0); AT_TR4(1, 1);
;         const bf16x8 ones = (bf16x8){0x3f80, 0x3f80, 0x3f80, 0x3f80, 0x3f80, 0x3f80, 0x3f80, 0x3f80};
; #pragma unroll
;         for (int c = 0; c < 2; ++c)
; #pragma unroll
;             for (int si = 0; si < 2; ++si) ol[c] = __builtin_amdgcn_mfma_f32_16x16x32_bf16(ones, pf[c][si], ol[c], 0, 0, 0); }
; #pragma unroll
;     for (int dt = 0; dt < 8; ++dt) {
;         if constexpr (PV) {
;             const int cb = dt % 3;
;             if (dt < 6) { AT_TR4((dt + 2) % 3, dt + 2); asm volatile("s_waitcnt lgkmcnt(8)" : "+v"(r[cb][0]), "+v"(r[cb][1]), "+v"(r[cb][2]), "+v"(r[cb][3])); }
;             else if (dt == 6) asm volatile("s_waitcnt lgkmcnt(4)" : "+v"(r[cb][0]), "+v"(r[cb][1]), "+v"(r[cb][2]), "+v"(r[cb][3]));
;             else asm volatile("s_waitcnt lgkmcnt(0)" : "+v"(r[cb][0]), "+v"(r[cb][1]), "+v"(r[cb][2]), "+v"(r[cb][3]));
; #pragma unroll
.Lat_yskip_p:
	s_setprio 0
	v_mov_b64_e32 v[140:141], s[6:7]
	v_mov_b64_e32 v[138:139], s[4:5]
	ds_read_b64_tr_b16 v[2:3], v192 offset:0
	ds_read_b64_tr_b16 v[4:5], v192 offset:0x1000
	ds_read_b64_tr_b16 v[10:11], v192 offset:0x2000
	ds_read_b64_tr_b16 v[12:13], v192 offset:0x3000
	v_exp_f32_e32 v154, v74
	s_nop 0
	v_mfma_f32_16x16x32_bf16 v[6:9], v[138:141], v[58:61], v[134:137]
	v_exp_f32_e32 v164, v75
	v_exp_f32_e32 v90, v90
	v_exp_f32_e32 v91, v91
	v_mfma_f32_16x16x32_bf16 v[134:137], v[138:141], v[34:37], v[6:9]
	ds_read_b64_tr_b16 v[6:7], v193 offset:0
	ds_read_b64_tr_b16 v[8:9], v193 offset:0x1000
	ds_read_b64_tr_b16 v[14:15], v193 offset:0x2000
	ds_read_b64_tr_b16 v[16:17], v193 offset:0x3000
	ds_read_b64_tr_b16 v[142:143], v194 offset:0
	ds_read_b64_tr_b16 v[144:145], v194 offset:0x1000
	ds_read_b64_tr_b16 v[146:147], v194 offset:0x2000
	ds_read_b64_tr_b16 v[148:149], v194 offset:0x3000
	s_waitcnt lgkmcnt(8)
	ds_read_b64_tr_b16 v[150:151], v195 offset:0
	ds_read_b64_tr_b16 v[152:153], v195 offset:0x1000
	v_mfma_f32_16x16x32_bf16 v[130:133], v[138:141], v[42:45], v[130:133]
	v_exp_f32_e32 v92, v92
	v_exp_f32_e32 v93, v93
	v_exp_f32_e32 v94, v94
	v_mfma_f32_16x16x32_bf16 v[126:129], v[2:5], v[58:61], v[126:129]
	v_exp_f32_e32 v95, v95
	v_exp_f32_e32 v96, v96
	v_exp_f32_e32 v97, v97
	v_mfma_f32_16x16x32_bf16 v[2:5], v[2:5], v[42:45], v[122:125]
	v_exp_f32_e32 v38, v38
	v_exp_f32_e32 v39, v39
	v_exp_f32_e32 v40, v40
	v_mfma_f32_16x16x32_bf16 v[122:125], v[10:13], v[34:37], v[126:129]
	v_exp_f32_e32 v41, v41
	v_exp_f32_e32 v62, v62
	v_exp_f32_e32 v63, v63
	v_mfma_f32_16x16x32_bf16 v[126:129], v[10:13], v[18:21], v[2:5]
	ds_read_b64_tr_b16 v[2:3], v195 offset:0x2000
	ds_read_b64_tr_b16 v[4:5], v195 offset:0x3000
	s_waitcnt lgkmcnt(8)
	v_mfma_f32_16x16x32_bf16 v[130:133], v[138:141], v[18:21], v[130:133]
	v_cvt_pk_bf16_f32 v38, v38, v39
	v_cvt_pk_bf16_f32 v39, v40, v41
	v_cvt_pk_bf16_f32 v40, v62, v63
	v_mfma_f32_16x16x32_bf16 v[10:13], v[6:9], v[58:61], v[114:117]
	s_add_i32 s43, s43, s30
	s_add_i32 s42, s42, s30
	s_cmpk_gt_i32 s43, 0x3ff
	v_mfma_f32_16x16x32_bf16 v[6:9], v[6:9], v[42:45], v[118:121]
	v_mfma_f32_16x16x32_bf16 v[118:121], v[14:17], v[34:37], v[10:13]
	ds_read_b64_tr_b16 v[10:11], v196 offset:0
	ds_read_b64_tr_b16 v[12:13], v196 offset:0x1000
	v_mfma_f32_16x16x32_bf16 v[114:117], v[14:17], v[18:21], v[6:9]
	ds_read_b64_tr_b16 v[14:15], v196 offset:0x2000
	ds_read_b64_tr_b16 v[16:17], v196 offset:0x3000
	s_waitcnt lgkmcnt(8)
	s_nop 0
	v_mfma_f32_16x16x32_bf16 v[6:9], v[142:145], v[58:61], v[106:109]
	v_mfma_f32_16x16x32_bf16 v[106:109], v[142:145], v[42:45], v[110:113]
	ds_read_b64_tr_b16 v[142:143], v197 offset:0
	ds_read_b64_tr_b16 v[144:145], v197 offset:0x1000
	v_mfma_f32_16x16x32_bf16 v[110:113], v[146:149], v[34:37], v[6:9]
	v_mfma_f32_16x16x32_bf16 v[106:109], v[146:149], v[18:21], v[106:109]
	ds_read_b64_tr_b16 v[146:147], v197 offset:0x2000
	ds_read_b64_tr_b16 v[148:149], v197 offset:0x3000
	s_waitcnt lgkmcnt(8)
	s_nop 0
	v_mfma_f32_16x16x32_bf16 v[6:9], v[150:153], v[58:61], v[98:101]
	s_nop 2
	v_exp_f32_e32 v98, v76
	v_exp_f32_e32 v99, v77
	v_mfma_f32_16x16x32_bf16 v[74:77], v[150:153], v[42:45], v[102:105]
	v_exp_f32_e32 v100, v86
	v_exp_f32_e32 v101, v87
	ds_read_b64_tr_b16 v[86:87], v198 offset:0
	v_mfma_f32_16x16x32_bf16 v[6:9], v[2:5], v[34:37], v[6:9]
	v_exp_f32_e32 v102, v88
	v_exp_f32_e32 v103, v89
	ds_read_b64_tr_b16 v[88:89], v198 offset:0x1000
	v_mfma_f32_16x16x32_bf16 v[2:5], v[2:5], v[18:21], v[74:77]
	ds_read_b64_tr_b16 v[74:75], v198 offset:0x2000
	ds_read_b64_tr_b16 v[76:77], v198 offset:0x3000
	s_waitcnt lgkmcnt(8)
	v_exp_f32_e32 v104, v22
	v_mfma_f32_16x16x32_bf16 v[78:81], v[10:13], v[58:61], v[78:81]
	v_exp_f32_e32 v105, v23
	v_exp_f32_e32 v150, v24
	v_mfma_f32_16x16x32_bf16 v[82:85], v[10:13], v[42:45], v[82:85]
	v_mfma_f32_16x16x32_bf16 v[10:13], v[14:17], v[34:37], v[78:81]
	ds_read_b64_tr_b16 v[78:79], v199 offset:0
	ds_read_b64_tr_b16 v[80:81], v199 offset:0x1000
	v_mfma_f32_16x16x32_bf16 v[14:17], v[14:17], v[18:21], v[82:85]
	ds_read_b64_tr_b16 v[82:83], v199 offset:0x2000
	ds_read_b64_tr_b16 v[84:85], v199 offset:0x3000
	s_waitcnt lgkmcnt(8)
	s_waitcnt lgkmcnt(4)
	s_nop 0
	v_mfma_f32_16x16x32_bf16 v[66:69], v[142:145], v[58:61], v[66:69]
	s_waitcnt lgkmcnt(0)
	v_mfma_f32_16x16x32_bf16 v[54:57], v[86:89], v[58:61], v[54:57]
	v_mfma_f32_16x16x32_bf16 v[58:61], v[78:81], v[58:61], v[30:33]
	v_mfma_f32_16x16x32_bf16 v[70:73], v[142:145], v[42:45], v[70:73]
	v_exp_f32_e32 v142, v25
	v_exp_f32_e32 v143, v26
	v_exp_f32_e32 v144, v27
	v_mfma_f32_16x16x32_bf16 v[22:25], v[146:149], v[34:37], v[66:69]
	v_cvt_pk_bf16_f32 v30, v90, v91
	v_cvt_pk_bf16_f32 v31, v92, v93
	v_cvt_pk_bf16_f32 v32, v94, v95
	v_exp_f32_e32 v66, v28
	v_exp_f32_e32 v67, v29
	v_mfma_f32_16x16x32_bf16 v[50:53], v[86:89], v[42:45], v[50:53]
	v_exp_f32_e32 v68, v64
	v_exp_f32_e32 v69, v65
	v_cvt_pk_bf16_f32 v33, v96, v97
	v_mfma_f32_16x16x32_bf16 v[54:57], v[74:77], v[34:37], v[54:57]
	v_cvt_pk_bf16_f32 v41, v68, v69
	v_mfma_f32_16x16x32_bf16 v[42:45], v[78:81], v[42:45], v[46:49]
	v_mfma_f32_16x16x32_bf16 v[46:49], v[82:85], v[34:37], v[58:61]
	v_cvt_pk_bf16_f32 v34, v154, v164
	v_cvt_pk_bf16_f32 v35, v98, v99
	v_cvt_pk_bf16_f32 v36, v100, v101
	v_cvt_pk_bf16_f32 v37, v102, v103
	v_mfma_f32_16x16x32_bf16 v[62:65], v[74:77], v[18:21], v[50:53]
	v_lshlrev_b32_e32 v154, 1, v156
	v_mfma_f32_16x16x32_bf16 v[58:61], v[138:141], v[34:37], v[134:137]
	s_nop 0
	v_cvt_pk_bf16_f32 v50, v104, v105
	v_cvt_pk_bf16_f32 v51, v150, v142
	v_cvt_pk_bf16_f32 v52, v143, v144
	v_cvt_pk_bf16_f32 v53, v66, v67
	v_mfma_f32_16x16x32_bf16 v[58:61], v[138:141], v[30:33], v[58:61]
	s_nop 0
	v_mfma_f32_16x16x32_bf16 v[78:81], v[138:141], v[50:53], v[130:133]
	v_mfma_f32_16x16x32_bf16 v[78:81], v[138:141], v[38:41], v[78:81]
	s_nop 4
	v_div_scale_f32 v59, s[2:3], v58, v58, 1.0
	v_mfma_f32_16x16x32_bf16 v[26:29], v[146:149], v[18:21], v[70:73]
	v_mfma_f32_16x16x32_bf16 v[18:21], v[82:85], v[18:21], v[42:45]
	v_rcp_f32_e32 v79, v59
	ds_read_b64_tr_b16 v[42:43], v200 offset:0
	ds_read_b64_tr_b16 v[44:45], v200 offset:0x1000
	ds_read_b64_tr_b16 v[66:67], v200 offset:0x2000
	ds_read_b64_tr_b16 v[68:69], v200 offset:0x3000
	ds_read_b64_tr_b16 v[70:71], v201 offset:0
	ds_read_b64_tr_b16 v[72:73], v201 offset:0x1000
	ds_read_b64_tr_b16 v[74:75], v201 offset:0x2000
	ds_read_b64_tr_b16 v[76:77], v201 offset:0x3000
	ds_read_b64_tr_b16 v[82:83], v202 offset:0
	ds_read_b64_tr_b16 v[84:85], v202 offset:0x1000
	ds_read_b64_tr_b16 v[86:87], v202 offset:0x2000
	ds_read_b64_tr_b16 v[88:89], v202 offset:0x3000
	s_nop 0
	s_waitcnt lgkmcnt(8)
; #define AT_TR4(slot, d) do { const unsigned _a = vaddr + (unsigned)vo[d]; AT_TR(r[slot][0], _a, 0); AT_TR(r[slot][1], _a, 16 * 256); AT_TR(r[slot][2], _a, 32 * 256); AT_TR(r[slot][3], _a, 48 * 256); } while (0)
; #define AT_TR4(slot, d) do { const unsigned _a = vaddr + (unsigned)vo[d]; AT_TR(r[slot][0], _a, 0); AT_TR(r[slot][1], _a, 16 * 256); AT_TR(r[slot][2], _a, 32 * 256); AT_TR(r[slot][3], _a, 48 * 256); } while (0)
; __device__ __forceinline__ void attn_pv(unsigned vaddr, const int (&vo)[8], const bf16x8 (&pf)[2][2], f32x4 (&o)[2][8], f32x4 (&ol)[2]) {
;     s16x4 r[3][4];
;     ...
;     AT_TR4(0, 0); AT_TR4(1, 1);
;     { const bf16x8 ones = (bf16x8){0x3f80, 0x3f80, 0x3f80, 0x3f80, 0x3f80, 0x3f80, 0x3f80, 0x3f80};
; #pragma unroll
;       for (int c = 0; c < 2; ++c)
; #pragma unroll
;           for (int si = 0; si < 2; ++si) ol[c] = __builtin_amdgcn_mfma_f32_16x16x32_bf16(ones, pf[c][si], ol[c], 0, 0, 0); }
; #pragma unroll
;     for (int dt = 0; dt < 8; ++dt) {
;         const int cb = dt % 3;
;         if (dt < 6) { AT_TR4((dt + 2) % 3, dt + 2); asm volatile("s_waitcnt lgkmcnt(8)" : "+v"(r[cb][0]), "+v"(r[cb][1]), "+v"(r[cb][2]), "+v"(r[cb][3])); }
;         else if (dt == 6) asm volatile("s_waitcnt lgkmcnt(4)" : "+v"(r[cb][0]), "+v"(r[cb][1]), "+v"(r[cb][2]), "+v"(r[cb][3]));
;         else asm volatile("s_waitcnt lgkmcnt(0)" : "+v"(r[cb][0]), "+v"(r[cb][1]), "+v"(r[cb][2]), "+v"(r[cb][3]));
; #pragma unroll
;         for (int si = 0; si < 2; ++si) {
;             const s16x4 lo = r[cb][2 * si], hi = r[cb][2 * si + 1];
;             const bf16x8 vf = (bf16x8){lo[0], lo[1], lo[2], lo[3], hi[0], hi[1], hi[2], hi[3]};
;             o[0][dt] = __builtin_amdgcn_mfma_f32_16x16x32_bf16(vf, pf[0][si], o[0][dt], 0, 0, 0);
;             o[1][dt] = __builtin_amdgcn_mfma_f32_16x16x32_bf16(vf, pf[1][si], o[1][dt], 0, 0, 0);
;         }
;     }
;     ...
; }
; __device__ __forceinline__ void attn_unit(LAS unsigned char* lds, int seq, int h, int qb, bf16_t* UQ, const bf16_t* KB, const bf16_t* VB, const float* rel_bias, const float* subln, float lam, float bmax) {
;     ...
;     const float i0 = 1.0f / ol[0][0], i1 = lam / ol[1][0];
;     float ss = 0.f;
; #pragma unroll
;     for (int dt = 0; dt < 8; ++dt)
; #pragma unroll
;         for (int j = 0; j < 4; ++j) { const float v = o[0][dt][j] * i0 - o[1][dt][j] * i1; o[0][dt][j] = v; ss += v * v; }
	ds_read_b64_tr_b16 v[90:91], v203 offset:0
	ds_read_b64_tr_b16 v[92:93], v203 offset:0x1000
	ds_read_b64_tr_b16 v[98:99], v203 offset:0x2000
	ds_read_b64_tr_b16 v[100:101], v203 offset:0x3000
	s_waitcnt lgkmcnt(8)
	s_nop 0
	v_mfma_f32_16x16x32_bf16 v[94:97], v[42:45], v[34:37], v[122:125]
	v_fma_f32 v60, -v59, v79, 1.0
	ds_read_b64_tr_b16 v[102:103], v204 offset:0
	ds_read_b64_tr_b16 v[104:105], v204 offset:0x1000
	v_mfma_f32_16x16x32_bf16 v[42:45], v[42:45], v[50:53], v[126:129]
	ds_read_b64_tr_b16 v[122:123], v204 offset:0x2000
	ds_read_b64_tr_b16 v[124:125], v204 offset:0x3000
	s_waitcnt lgkmcnt(8)
	v_mfma_f32_16x16x32_bf16 v[118:121], v[70:73], v[34:37], v[118:121]
	v_fmac_f32_e32 v79, v60, v79
	v_div_scale_f32 v60, vcc, 1.0, v58, 1.0
	v_mfma_f32_16x16x32_bf16 v[70:73], v[70:73], v[50:53], v[114:117]
	v_mfma_f32_16x16x32_bf16 v[110:113], v[82:85], v[34:37], v[110:113]
	v_mfma_f32_16x16x32_bf16 v[80:83], v[82:85], v[50:53], v[106:109]
	v_mul_f32_e32 v84, v60, v79
	v_fma_f32 v61, -v59, v84, v60
	v_fmac_f32_e32 v84, v61, v79
	v_mfma_f32_16x16x32_bf16 v[94:97], v[66:69], v[30:33], v[94:97]
	v_fma_f32 v59, -v59, v84, v60
	v_div_fmas_f32 v59, v59, v79, v84
	v_mfma_f32_16x16x32_bf16 v[42:45], v[66:69], v[38:41], v[42:45]
	ds_read_b64_tr_b16 v[66:67], v205 offset:0
	ds_read_b64_tr_b16 v[68:69], v205 offset:0x1000
	ds_read_b64_tr_b16 v[126:127], v205 offset:0x2000
	ds_read_b64_tr_b16 v[128:129], v205 offset:0x3000
	s_waitcnt lgkmcnt(8)
	ds_read_b64_tr_b16 v[130:131], v206 offset:0
	ds_read_b64_tr_b16 v[132:133], v206 offset:0x1000
	ds_read_b64_tr_b16 v[114:115], v206 offset:0x2000
	ds_read_b64_tr_b16 v[116:117], v206 offset:0x3000
	v_mfma_f32_16x16x32_bf16 v[118:121], v[74:77], v[30:33], v[118:121]
	s_waitcnt lgkmcnt(8)
	ds_read_b64_tr_b16 v[134:135], v207 offset:0
	ds_read_b64_tr_b16 v[136:137], v207 offset:0x1000
	v_mfma_f32_16x16x32_bf16 v[70:73], v[74:77], v[38:41], v[70:73]
	ds_read_b64_tr_b16 v[74:75], v207 offset:0x2000
	ds_read_b64_tr_b16 v[76:77], v207 offset:0x3000
	s_waitcnt lgkmcnt(8)
	s_waitcnt lgkmcnt(4)
	v_mfma_f32_16x16x32_bf16 v[2:5], v[90:93], v[50:53], v[2:5]
	s_waitcnt lgkmcnt(0)
	v_mfma_f32_16x16x32_bf16 v[60:63], v[130:133], v[50:53], v[62:65]
	s_nop 2
	v_div_scale_f32 v65, s[2:3], v78, v78, v174
	v_rcp_f32_e32 v85, v65
	v_mfma_f32_16x16x32_bf16 v[18:21], v[134:137], v[50:53], v[18:21]
	v_div_fixup_f32 v64, v59, v58, 1.0
	v_fma_f32 v79, -v65, v85, 1.0
	v_mfma_f32_16x16x32_bf16 v[58:61], v[114:117], v[38:41], v[60:63]
	v_fmac_f32_e32 v85, v79, v85
	s_nop 1
	v_div_scale_f32 v62, vcc, v174, v78, v174
	v_mfma_f32_16x16x32_bf16 v[46:49], v[134:137], v[34:37], v[46:49]
	v_mul_f32_e32 v63, v62, v85
	v_fma_f32 v79, -v65, v63, v62
	v_fmac_f32_e32 v63, v79, v85
	v_mfma_f32_16x16x32_bf16 v[18:21], v[74:77], v[38:41], v[18:21]
	v_fma_f32 v62, -v65, v63, v62
	v_div_fmas_f32 v62, v62, v85, v63
	v_div_fixup_f32 v78, v62, v78, v174
	v_mfma_f32_16x16x32_bf16 v[46:49], v[74:77], v[30:33], v[46:49]
	v_mul_f32_e64 v42, v78, v42
	v_mul_f32_e64 v43, v78, v43
	s_nop 1
	v_pk_mul_f32 v[18:19], v[78:79], v[18:19] op_sel_hi:[0,1]
	v_pk_fma_f32 v[42:43], v[64:65], v[94:95], v[42:43] op_sel_hi:[0,1,1] neg_lo:[0,0,1] neg_hi:[0,0,1]
	v_mfma_f32_16x16x32_bf16 v[6:9], v[90:93], v[34:37], v[6:9]
	v_mul_f32_e64 v44, v78, v44
	v_mul_f32_e64 v45, v78, v45
	v_pk_fma_f32 v[46:47], v[64:65], v[46:47], v[18:19] op_sel_hi:[0,1,1] neg_lo:[0,0,1] neg_hi:[0,0,1]
	v_pk_mul_f32 v[18:19], v[78:79], v[20:21] op_sel_hi:[0,1]
	v_pk_fma_f32 v[48:49], v[64:65], v[48:49], v[18:19] op_sel_hi:[0,1,1] neg_lo:[0,0,1] neg_hi:[0,0,1]
	global_load_dwordx4 v[18:21], v[158:159], off
	v_mfma_f32_16x16x32_bf16 v[2:5], v[98:101], v[38:41], v[2:5]
	v_mul_f32_e64 v60, v78, v60
	v_mul_f32_e64 v61, v78, v61
	v_pk_fma_f32 v[44:45], v[64:65], v[96:97], v[44:45] op_sel_hi:[0,1,1] neg_lo:[0,0,1] neg_hi:[0,0,1]
	v_pk_mul_f32 v[84:85], v[42:43], v[42:43]
	v_mfma_f32_16x16x32_bf16 v[54:57], v[130:133], v[34:37], v[54:57]
	v_mul_f32_e64 v70, v78, v70
	v_mul_f32_e64 v71, v78, v71
	s_nop 0
	v_pk_mul_f32 v[4:5], v[78:79], v[4:5] op_sel_hi:[0,1]
	v_pk_fma_f32 v[70:71], v[64:65], v[118:119], v[70:71] op_sel_hi:[0,1,1] neg_lo:[0,0,1] neg_hi:[0,0,1]
	v_mfma_f32_16x16x32_bf16 v[6:9], v[98:101], v[30:33], v[6:9]
	v_mul_f32_e64 v72, v78, v72
	v_mul_f32_e64 v73, v78, v73
	v_pk_fma_f32 v[72:73], v[64:65], v[120:121], v[72:73] op_sel_hi:[0,1,1] neg_lo:[0,0,1] neg_hi:[0,0,1]
	v_pk_mul_f32 v[76:77], v[46:47], v[46:47]
	v_mfma_f32_16x16x32_bf16 v[54:57], v[114:117], v[30:33], v[54:57]
	v_mfma_f32_16x16x32_bf16 v[10:13], v[102:105], v[34:37], v[10:13]
	s_nop 1
	v_fma_f32 v94, v64, v8, -v4
	v_fma_f32 v95, v64, v9, -v5
	v_pk_mul_f32 v[8:9], v[78:79], v[2:3] op_sel_hi:[0,1]
	s_nop 1
	v_pk_fma_f32 v[56:57], v[64:65], v[56:57], v[60:61] op_sel_hi:[0,1,1] neg_lo:[0,0,1] neg_hi:[0,0,1]
	v_mfma_f32_16x16x32_bf16 v[2:5], v[66:69], v[34:37], v[22:25]
	v_mul_f32_e64 v96, v94, v94
	v_mul_f32_e64 v97, v95, v95
	v_pk_mul_f32 v[74:75], v[56:57], v[56:57]
	v_mfma_f32_16x16x32_bf16 v[106:109], v[86:89], v[30:33], v[110:113]
	v_fma_f32 v22, v64, v6, -v8
	v_fma_f32 v23, v64, v7, -v9
	v_pk_mul_f32 v[24:25], v[22:23], v[22:23]
	v_mfma_f32_16x16x32_bf16 v[60:63], v[86:89], v[38:41], v[80:83]
	v_mul_f32_e64 v88, v70, v70
	v_mul_f32_e64 v89, v71, v71
	v_pk_mul_f32 v[86:87], v[72:73], v[72:73]
	v_pk_mul_f32 v[82:83], v[44:45], v[44:45]
	v_mfma_f32_16x16x32_bf16 v[10:13], v[122:125], v[30:33], v[10:13]
	s_nop 2
	v_mul_f32_e64 v60, v78, v60
	v_mul_f32_e64 v61, v78, v61
	v_pk_fma_f32 v[60:61], v[64:65], v[106:107], v[60:61] op_sel_hi:[0,1,1] neg_lo:[0,0,1] neg_hi:[0,0,1]
	v_pk_mul_f32 v[62:63], v[78:79], v[62:63] op_sel_hi:[0,1]
; __device__ __forceinline__ unsigned cvtpk(float lo, float hi) { f32x2 v = {lo, hi}; bf16x2_t b = __builtin_convertvector(v, bf16x2_t); return __builtin_bit_cast(unsigned, b); }
; #define AT_BAR(N) asm volatile("s_waitcnt vmcnt(" #N ") lgkmcnt(0)\n\ts_barrier" ::: "memory")
; __device__ __forceinline__ void attn_unit(LAS unsigned char* lds, int seq, int h, int qb, bf16_t* UQ, const bf16_t* KB, const bf16_t* VB, const float* rel_bias, const float* subln, float lam, float bmax) {
;     ...
;     const float i0 = 1.0f / ol[0][0], i1 = lam / ol[1][0];
;     float ss = 0.f;
; #pragma unroll
;     for (int dt = 0; dt < 8; ++dt)
; #pragma unroll
;         for (int j = 0; j < 4; ++j) { const float v = o[0][dt][j] * i0 - o[1][dt][j] * i1; o[0][dt][j] = v; ss += v * v; }
;     ss += __shfl_xor(ss, 16); ss += __shfl_xor(ss, 32);
;     const float rs = __builtin_amdgcn_rsqf(ss * (1.0f / 128.0f) + EPS) * 0.8f;
;     bf16_t* op = UQ + (size_t)(row0 + q0 + 16 * w + r16) * DM + 512 + 128 * h + 4 * fq;
; #pragma unroll
;     for (int dt = 0; dt < 8; ++dt) {
;         const f32x4 gsl = *(const f32x4*)(subln + 16 * dt + 4 * fq);
;         u32x2 wv; wv.x = cvtpk(o[0][dt][0] * rs * gsl[0], o[0][dt][1] * rs * gsl[1]); wv.y = cvtpk(o[0][dt][2] * rs * gsl[2], o[0][dt][3] * rs * gsl[3]);
;         *(u32x2*)(op + 16 * dt) = wv;
;     }
;     AT_BAR(0);
	v_mfma_f32_16x16x32_bf16 v[2:5], v[126:129], v[30:33], v[2:5]
	v_add_f32_e32 v30, v84, v85
	v_add_f32_e32 v30, v82, v30
	v_add_f32_e32 v30, v83, v30
	v_add_f32_e32 v30, v30, v88
	v_mfma_f32_16x16x32_bf16 v[14:17], v[102:105], v[50:53], v[14:17]
	v_add_f32_e32 v30, v89, v30
	v_add_f32_e32 v30, v86, v30
	v_pk_mul_f32 v[92:93], v[60:61], v[60:61]
	v_add_f32_e32 v30, v87, v30
	v_pk_fma_f32 v[62:63], v[64:65], v[108:109], v[62:63] op_sel_hi:[0,1,1] neg_lo:[0,0,1] neg_hi:[0,0,1]
	v_add_f32_e32 v30, v30, v92
	v_pk_mul_f32 v[90:91], v[62:63], v[62:63]
	v_mfma_f32_16x16x32_bf16 v[14:17], v[122:125], v[38:41], v[14:17]
	v_add_f32_e32 v30, v93, v30
	v_add_f32_e32 v30, v90, v30
	v_add_f32_e32 v30, v91, v30
	v_mfma_f32_16x16x32_bf16 v[6:9], v[66:69], v[50:53], v[26:29]
	v_add_f32_e32 v24, v30, v24
	s_nop 2
	v_pk_mul_f32 v[14:15], v[78:79], v[14:15] op_sel_hi:[0,1]
	v_add_f32_e32 v24, v25, v24
	v_mfma_f32_16x16x32_bf16 v[6:9], v[126:129], v[38:41], v[6:9]
	v_fma_f32 v10, v64, v10, -v14
	v_fma_f32 v11, v64, v11, -v15
	v_add_f32_e32 v24, v96, v24
	v_pk_mul_f32 v[16:17], v[78:79], v[16:17] op_sel_hi:[0,1]
	v_pk_mul_f32 v[14:15], v[10:11], v[10:11]
	v_add_f32_e32 v24, v97, v24
	v_pk_fma_f32 v[12:13], v[64:65], v[12:13], v[16:17] op_sel_hi:[0,1,1] neg_lo:[0,0,1] neg_hi:[0,0,1]
	v_add_f32_e32 v14, v24, v14
	v_pk_mul_f32 v[16:17], v[12:13], v[12:13]
	v_pk_mul_f32 v[6:7], v[78:79], v[6:7] op_sel_hi:[0,1]
	v_add_f32_e32 v14, v15, v14
	v_pk_fma_f32 v[6:7], v[64:65], v[2:3], v[6:7] op_sel_hi:[0,1,1] neg_lo:[0,0,1] neg_hi:[0,0,1]
	v_add_f32_e32 v14, v16, v14
	v_pk_mul_f32 v[8:9], v[78:79], v[8:9] op_sel_hi:[0,1]
	v_pk_mul_f32 v[2:3], v[6:7], v[6:7]
	v_add_f32_e32 v14, v17, v14
	v_pk_fma_f32 v[8:9], v[64:65], v[4:5], v[8:9] op_sel_hi:[0,1,1] neg_lo:[0,0,1] neg_hi:[0,0,1]
	v_add_f32_e32 v2, v14, v2
	v_pk_mul_f32 v[4:5], v[8:9], v[8:9]
	v_pk_mul_f32 v[26:27], v[78:79], v[58:59] op_sel_hi:[0,1]
	v_add_f32_e32 v2, v3, v2
	v_pk_fma_f32 v[26:27], v[64:65], v[54:55], v[26:27] op_sel_hi:[0,1,1] neg_lo:[0,0,1] neg_hi:[0,0,1]
	v_add_f32_e32 v2, v4, v2
	v_pk_mul_f32 v[28:29], v[26:27], v[26:27]
	v_add_f32_e32 v2, v5, v2
	v_add_f32_e32 v2, v2, v28
	v_add_f32_e32 v2, v29, v2
	v_add_f32_e32 v2, v74, v2
	v_add_f32_e32 v2, v75, v2
	v_add_f32_e32 v2, v2, v76
	v_pk_mul_f32 v[80:81], v[48:49], v[48:49]
	v_add_f32_e32 v2, v77, v2
	v_add_f32_e32 v2, v80, v2
	v_add_f32_e32 v2, v81, v2
	ds_bpermute_b32 v3, v1, v2
	v_lshl_add_u64 v[14:15], v[162:163], 0, v[154:155]
	s_waitcnt lgkmcnt(0)
	v_add_f32_e32 v2, v2, v3
	ds_bpermute_b32 v3, v157, v2
	s_waitcnt lgkmcnt(0)
	v_add_f32_e32 v2, v2, v3
	v_fmamk_f32 v2, v2, 0x3c000000, v209
	v_rsq_f32_e32 v2, v2
	s_nop 0
	v_mul_f32_e32 v16, 0x3f4ccccd, v2
	v_pk_mul_f32 v[2:3], v[42:43], v[16:17] op_sel_hi:[1,0]
	v_pk_mul_f32 v[4:5], v[44:45], v[16:17] op_sel_hi:[1,0]
	s_waitcnt vmcnt(0)
	v_pk_mul_f32 v[2:3], v[18:19], v[2:3]
	v_pk_mul_f32 v[4:5], v[20:21], v[4:5]
	v_cvt_pk_bf16_f32 v2, v2, v3
	v_cvt_pk_bf16_f32 v3, v4, v5
	global_store_dwordx2 v[14:15], v[2:3], off offset:1024
	global_load_dwordx4 v[216:219], v[158:159], off offset:64
	global_load_dwordx4 v[220:223], v[158:159], off offset:128
	global_load_dwordx4 v[224:227], v[158:159], off offset:192
	global_load_dwordx4 v[228:231], v[158:159], off offset:256
	global_load_dwordx4 v[232:235], v[158:159], off offset:320
	global_load_dwordx4 v[236:239], v[158:159], off offset:384
	global_load_dwordx4 v[240:243], v[158:159], off offset:448
	v_pk_mul_f32 v[18:19], v[70:71], v[16:17] op_sel_hi:[1,0]
	v_pk_mul_f32 v[20:21], v[94:95], v[16:17] op_sel_hi:[1,0]
	v_pk_mul_f32 v[10:11], v[10:11], v[16:17] op_sel_hi:[1,0]
	v_pk_mul_f32 v[12:13], v[12:13], v[16:17] op_sel_hi:[1,0]
	v_pk_mul_f32 v[6:7], v[6:7], v[16:17] op_sel_hi:[1,0]
	v_pk_mul_f32 v[8:9], v[8:9], v[16:17] op_sel_hi:[1,0]
	s_waitcnt vmcnt(6)
	v_pk_mul_f32 v[2:3], v[216:217], v[18:19]
	v_pk_mul_f32 v[18:19], v[72:73], v[16:17] op_sel_hi:[1,0]
	v_cvt_pk_bf16_f32 v2, v2, v3
	v_pk_mul_f32 v[4:5], v[218:219], v[18:19]
	v_pk_mul_f32 v[18:19], v[60:61], v[16:17] op_sel_hi:[1,0]
	v_cvt_pk_bf16_f32 v3, v4, v5
	global_store_dwordx2 v[14:15], v[2:3], off offset:1056
	s_waitcnt vmcnt(6)
	v_pk_mul_f32 v[2:3], v[220:221], v[18:19]
	v_pk_mul_f32 v[18:19], v[62:63], v[16:17] op_sel_hi:[1,0]
	v_cvt_pk_bf16_f32 v2, v2, v3
	v_pk_mul_f32 v[4:5], v[222:223], v[18:19]
	v_pk_mul_f32 v[18:19], v[22:23], v[16:17] op_sel_hi:[1,0]
	v_cvt_pk_bf16_f32 v3, v4, v5
	global_store_dwordx2 v[14:15], v[2:3], off offset:1088
	s_waitcnt vmcnt(6)
	v_pk_mul_f32 v[2:3], v[224:225], v[18:19]
	v_pk_mul_f32 v[4:5], v[226:227], v[20:21]
	v_cvt_pk_bf16_f32 v2, v2, v3
	v_cvt_pk_bf16_f32 v3, v4, v5
	global_store_dwordx2 v[14:15], v[2:3], off offset:1120
	s_waitcnt vmcnt(6)
	v_pk_mul_f32 v[2:3], v[228:229], v[10:11]
	v_pk_mul_f32 v[4:5], v[230:231], v[12:13]
	v_cvt_pk_bf16_f32 v2, v2, v3
	v_cvt_pk_bf16_f32 v3, v4, v5
	global_store_dwordx2 v[14:15], v[2:3], off offset:1152
	s_waitcnt vmcnt(6)
	v_pk_mul_f32 v[2:3], v[232:233], v[6:7]
	v_pk_mul_f32 v[4:5], v[234:235], v[8:9]
	v_cvt_pk_bf16_f32 v2, v2, v3
	v_cvt_pk_bf16_f32 v3, v4, v5
	global_store_dwordx2 v[14:15], v[2:3], off offset:1184
	v_pk_mul_f32 v[6:7], v[26:27], v[16:17] op_sel_hi:[1,0]
	v_pk_mul_f32 v[8:9], v[56:57], v[16:17] op_sel_hi:[1,0]
	s_waitcnt vmcnt(6)
	v_pk_mul_f32 v[2:3], v[236:237], v[6:7]
	v_pk_mul_f32 v[4:5], v[238:239], v[8:9]
	v_cvt_pk_bf16_f32 v2, v2, v3
	v_cvt_pk_bf16_f32 v3, v4, v5
	global_store_dwordx2 v[14:15], v[2:3], off offset:1216
	v_pk_mul_f32 v[6:7], v[46:47], v[16:17] op_sel_hi:[1,0]
	v_pk_mul_f32 v[8:9], v[48:49], v[16:17] op_sel_hi:[1,0]
	s_waitcnt vmcnt(6)
	v_pk_mul_f32 v[2:3], v[6:7], v[240:241]
	v_pk_mul_f32 v[4:5], v[8:9], v[242:243]
	v_cvt_pk_bf16_f32 v2, v2, v3
	v_cvt_pk_bf16_f32 v3, v4, v5
	global_store_dwordx2 v[14:15], v[2:3], off offset:1248
	s_waitcnt vmcnt(0) lgkmcnt(0)
	s_barrier
	s_cbranch_scc1 .LBB0_540

; __device__ __forceinline__ void attn_unit(LAS unsigned char* lds, int seq, int h, int qb, bf16_t* UQ, const bf16_t* KB, const bf16_t* VB, const float* rel_bias, const float* subln, float lam, float bmax) {
;     const int tid = threadIdx.x, lane = tid & 63, w = __builtin_amdgcn_readfirstlane(tid >> 6), r16 = lane & 15, fq = lane >> 4;
;     int row0, S; if (seq < NSEQ_P) { row0 = seq * SEQ_P; S = SEQ_P; } else { row0 = MP + (seq - NSEQ_P) * SEQ_S; S = SEQ_S; }
;     const int q0 = qb * 128, NT = S / 64, tmask = NT - 1, tstart = 2 * qb;
;     const LAS unsigned char* tab = lds + AT_TAB;
;     const unsigned lds0 = (unsigned)(size_t)lds;
;     if (tid < 257) ((LAS float*)(lds + AT_TAB))[tid] = LOG2E * (rel_bias[t5_bucket(tid - 128) * 4 + h] - bmax);
;     bf16x8 qf[2][2];
;     { const bf16_t* qp = UQ + (size_t)(row0 + q0 + 16 * w + r16) * DM + 512 + 128 * h + 8 * fq;
; #pragma unroll
;       for (int c = 0; c < 2; ++c)
; #pragma unroll
;           for (int kk = 0; kk < 2; ++kk) qf[c][kk] = *(const bf16x8*)(qp + 64 * c + 32 * kk); }
;     f32x4 o[2][8];
; #pragma unroll
;     for (int c = 0; c < 2; ++c)
; #pragma unroll
;         for (int d = 0; d < 8; ++d) o[c][d] = (f32x4){0.f, 0.f, 0.f, 0.f};
;     f32x4 ol[2] = {(f32x4){0.f, 0.f, 0.f, 0.f}, (f32x4){0.f, 0.f, 0.f, 0.f}};
;     unsigned kso[2], vso[2];
; #pragma unroll
;     for (int i = 0; i < 2; ++i) { const int row = 4 * (2 * w + i) + (lane >> 4), pos = lane & 15;
;         kso[i] = (unsigned)(row * 512 + 8 * (pos ^ (row & 15))) * 2u; vso[i] = (unsigned)(row * 512 + 8 * (pos ^ (2 * (row & 7)))) * 2u; }
;     const char* kg = (const char*)(KB + (size_t)row0 * 512 + 128 * h);
;     const char* vg = (const char*)(VB + (size_t)row0 * 512 + 128 * h);
;     ...
;     AT_STAGE(kg, kso, 0, AT_K0); AT_STAGE(vg, vso, 0, AT_V0); AT_STAGE(kg, kso, 1, AT_K0 + AT_TILE); AT_STAGE(vg, vso, 1, AT_V0 + AT_TILE); AT_STAGE(kg, kso, 2, AT_K0 + 2 * AT_TILE);
;     int kfo[2][2], vo[8];
; #pragma unroll
;     for (int c = 0; c < 2; ++c)
; #pragma unroll
;         for (int kk = 0; kk < 2; ++kk) kfo[c][kk] = r16 * 256 + (((8 * c + 4 * kk + fq) ^ r16) * 16);
;     { const int rk = 4 * (fq & 1) + (r16 >> 2);
; #pragma unroll
;       for (int dt = 0; dt < 8; ++dt) vo[dt] = (4 * fq + (r16 >> 2)) * 256 + ((dt ^ rk) * 32) + (r16 & 3) * 8; }
;     const int qrow = q0 + 16 * w;
;     const int tixb = (4 * fq - (qrow + r16) + 128) * 4;
.LBB0_533:
	v_exp_f32_e32 v82, v42
	v_exp_f32_e32 v83, v43
	v_exp_f32_e32 v84, v44
	v_exp_f32_e32 v85, v45
	ds_read_b128 v[42:45], v67 offset:16384
	v_exp_f32_e32 v94, v22
	v_exp_f32_e32 v95, v23
	v_exp_f32_e32 v96, v24
	v_exp_f32_e32 v97, v25
	ds_read_b128 v[22:25], v69 offset:16384
	v_exp_f32_e32 v98, v46
	v_exp_f32_e32 v99, v47
	v_exp_f32_e32 v100, v48
	v_exp_f32_e32 v101, v49
	ds_read_b128 v[46:49], v66 offset:16384
	ds_read_b128 v[70:73], v67 offset:20480
	s_waitcnt lgkmcnt(0)
	v_mfma_f32_16x16x32_bf16 v[42:45], v[42:45], v[2:5], v[58:61]
	v_exp_f32_e32 v102, v38
	v_exp_f32_e32 v103, v39
	v_exp_f32_e32 v104, v40
	v_exp_f32_e32 v105, v41
	ds_read_b128 v[38:41], v68 offset:16384
	ds_read_b128 v[78:81], v69 offset:20480
	v_mfma_f32_16x16x32_bf16 v[74:77], v[22:25], v[6:9], v[42:45]
	v_exp_f32_e32 v106, v18
	v_exp_f32_e32 v107, v19
	v_exp_f32_e32 v108, v28
	ds_read_b128 v[42:45], v66 offset:20480
	v_mfma_f32_16x16x32_bf16 v[22:25], v[46:49], v[10:13], v[58:61]
	v_exp_f32_e32 v109, v29
	s_and_b32 s2, s42, 15
	s_lshl_b32 s50, s2, 1
	v_exp_f32_e32 v58, v20
	v_exp_f32_e32 v59, v21
	ds_read_b128 v[18:21], v68 offset:20480
	s_waitcnt lgkmcnt(0)
	v_mfma_f32_16x16x32_bf16 v[22:25], v[38:41], v[14:17], v[22:25]
	v_exp_f32_e32 v60, v26
	v_exp_f32_e32 v61, v27
	s_add_i32 s50, s50, 2
	v_mfma_f32_16x16x32_bf16 v[38:41], v[70:73], v[2:5], v[50:53]
	v_exp_f32_e32 v70, v30
	v_exp_f32_e32 v71, v31
	v_exp_f32_e32 v72, v32
	v_exp_f32_e32 v73, v33
	ds_read_b128 v[30:33], v67 offset:24576
	v_mfma_f32_16x16x32_bf16 v[86:89], v[78:81], v[6:9], v[38:41]
	v_exp_f32_e32 v78, v34
	v_exp_f32_e32 v79, v35
	v_exp_f32_e32 v80, v36
	ds_read_b128 v[38:41], v69 offset:24576
	v_mfma_f32_16x16x32_bf16 v[26:29], v[42:45], v[10:13], v[50:53]
	ds_read_b128 v[42:45], v66 offset:24576
	ds_read_b128 v[46:49], v67 offset:28672
	v_exp_f32_e32 v67, v37
	s_addk_i32 s51, 0xff42
	v_mfma_f32_16x16x32_bf16 v[26:29], v[18:21], v[14:17], v[26:29]
	s_add_i32 s52, s44, 3
	s_movk_i32 s55, 0x4000
	s_mov_b32 s54, 0x8000
	s_waitcnt lgkmcnt(0)
	v_mfma_f32_16x16x32_bf16 v[18:21], v[30:33], v[2:5], v[62:65]
	ds_read_b128 v[30:33], v68 offset:24576
	ds_read_b128 v[50:53], v69 offset:28672
	s_mov_b32 s53, 0x10000
	s_mov_b32 s56, 0
	v_mfma_f32_16x16x32_bf16 v[90:93], v[38:41], v[6:9], v[18:21]
	s_mov_b32 s2, 0
	s_nop 1
	v_cvt_pk_bf16_f32 v18, v70, v71
	v_cvt_pk_bf16_f32 v19, v72, v73
	ds_read_b128 v[70:73], v66 offset:28672
	v_mfma_f32_16x16x32_bf16 v[34:37], v[42:45], v[10:13], v[62:65]
	v_cvt_pk_bf16_f32 v20, v78, v79
	v_cvt_pk_bf16_f32 v21, v80, v67
	v_cvt_pk_bf16_f32 v42, v106, v107
	ds_read_b128 v[62:65], v68 offset:28672
	s_waitcnt lgkmcnt(0)
	v_mfma_f32_16x16x32_bf16 v[38:41], v[30:33], v[14:17], v[34:37]
	s_waitcnt vmcnt(4) lgkmcnt(0)
	s_barrier
	v_cvt_pk_bf16_f32 v43, v58, v59
	v_cvt_pk_bf16_f32 v44, v60, v61
	v_mfma_f32_16x16x32_bf16 v[30:33], v[46:49], v[2:5], v[54:57]
	v_cvt_pk_bf16_f32 v34, v94, v95
	v_cvt_pk_bf16_f32 v35, v96, v97
	v_cvt_pk_bf16_f32 v45, v108, v109
	v_mfma_f32_16x16x32_bf16 v[94:97], v[50:53], v[6:9], v[30:33]
	v_cvt_pk_bf16_f32 v36, v102, v103
	v_cvt_pk_bf16_f32 v37, v104, v105
	v_cvt_pk_bf16_f32 v58, v82, v83
	v_mfma_f32_16x16x32_bf16 v[30:33], v[70:73], v[10:13], v[54:57]
	v_cvt_pk_bf16_f32 v59, v84, v85
	v_cvt_pk_bf16_f32 v60, v98, v99
	v_cvt_pk_bf16_f32 v61, v100, v101
	v_mfma_f32_16x16x32_bf16 v[62:65], v[62:65], v[14:17], v[30:33]
	s_nop 3
	v_mov_b32_e32 v30, 0
	v_mov_b32_e32 v31, v30
	v_mov_b32_e32 v32, v30
	v_mov_b32_e32 v33, v30
	v_mov_b32_e32 v46, v30
	v_mov_b32_e32 v47, v30
	v_mov_b32_e32 v48, v30
	v_mov_b32_e32 v49, v30
	v_mov_b32_e32 v54, v30
	v_mov_b32_e32 v55, v30
	v_mov_b32_e32 v56, v30
	v_mov_b32_e32 v57, v30
	v_mov_b32_e32 v50, v30
	v_mov_b32_e32 v51, v30
	v_mov_b32_e32 v52, v30
	v_mov_b32_e32 v53, v30
	v_mov_b32_e32 v66, v30
	v_mov_b32_e32 v67, v30
	v_mov_b32_e32 v68, v30
	v_mov_b32_e32 v69, v30
	v_mov_b32_e32 v70, v30
	v_mov_b32_e32 v71, v30
	v_mov_b32_e32 v72, v30
	v_mov_b32_e32 v73, v30
	v_mov_b32_e32 v78, v30
	v_mov_b32_e32 v79, v30
	v_mov_b32_e32 v80, v30
	v_mov_b32_e32 v81, v30
	v_mov_b32_e32 v82, v30
	v_mov_b32_e32 v83, v30
	v_mov_b32_e32 v84, v30
	v_mov_b32_e32 v85, v30
	v_mov_b32_e32 v98, v30
	v_mov_b32_e32 v99, v30
	v_mov_b32_e32 v100, v30
	v_mov_b32_e32 v101, v30
	v_mov_b32_e32 v102, v30
	v_mov_b32_e32 v103, v30
	v_mov_b32_e32 v104, v30
	v_mov_b32_e32 v105, v30
	v_mov_b32_e32 v106, v30
	v_mov_b32_e32 v107, v30
	v_mov_b32_e32 v108, v30
	v_mov_b32_e32 v109, v30
	v_mov_b32_e32 v110, v30
	v_mov_b32_e32 v111, v30
	v_mov_b32_e32 v112, v30
	v_mov_b32_e32 v113, v30
	v_mov_b32_e32 v114, v30
	v_mov_b32_e32 v115, v30
	v_mov_b32_e32 v116, v30
	v_mov_b32_e32 v117, v30
	v_mov_b32_e32 v118, v30
	v_mov_b32_e32 v119, v30
	v_mov_b32_e32 v120, v30
	v_mov_b32_e32 v121, v30
	v_mov_b32_e32 v122, v30
	v_mov_b32_e32 v123, v30
	v_mov_b32_e32 v124, v30
	v_mov_b32_e32 v125, v30
	v_mov_b32_e32 v134, v30
	v_mov_b32_e32 v135, v30
	v_mov_b32_e32 v136, v30
	v_mov_b32_e32 v137, v30
	v_mov_b32_e32 v130, v30
	v_mov_b32_e32 v131, v30
	v_mov_b32_e32 v132, v30
	v_mov_b32_e32 v133, v30
	v_mov_b32_e32 v126, v30
	v_mov_b32_e32 v127, v30
	v_mov_b32_e32 v128, v30
	v_mov_b32_e32 v129, v30
	v_readfirstlane_b32 s98, v171
	s_nop 3
	s_lshr_b32 s98, s98, 6
	s_cmp_lt_u32 s98, 4
	s_cbranch_scc1 .Lat_xskip_p
	s_setprio 1
	s_barrier
